# select phase: key loads rewritten with full memory-level parallelism (112 loads in flight instead of 72 serialized round trips) + skip 16-word chunks beyond causal limit
# speedup vs baseline: 1.0359x; 1.0234x over previous
.LBB0_673:
	s_cmpk_gt_i32 s2, 0xfff
	s_cbranch_scc1 .LBB0_672
	v_lshl_add_u32 v87, s2, 2, v77
	v_ashrrev_i32_e32 v153, 1, v87
	v_sub_u32_e32 v87, 0x1fff, v153
	v_ashrrev_i32_e32 v88, 5, v87
	v_readfirstlane_b32 s100, v87
	s_nop 3
	s_lshr_b32 s100, s100, 6
	s_add_u32 s100, s100, 16
	s_lshr_b32 s100, s100, 4
	s_mov_b32 m0, s100
	v_add_u32_e32 v93, 1, v88
	v_mad_i64_i32 v[88:89], s[2:3], v88, v93, 0
	v_lshlrev_b64 v[90:91], 9, v[88:89]
	v_and_b32_e32 v92, 31, v87
	v_and_b32_e32 v91, 0x3fffffff, v91
	v_and_b32_e32 v90, 0xfffffc00, v90
	v_lshlrev_b32_e32 v93, 5, v93
	v_lshl_add_u64 v[90:91], v[90:91], 2, v[8:9]
	v_mad_i64_i32 v[114:115], s[2:3], v93, v92, 0
	v_lshl_add_u64 v[90:91], v[114:115], 2, v[90:91]
	s_movk_i32 s2, 0x1f00
	s_mov_b32 s39, 0
	v_mov_b32_e32 v240, 0
	v_readfirstlane_b32 s100, v90
	v_readfirstlane_b32 s101, v91
	v_lshlrev_b32_e32 v212, 2, v2
	v_lshlrev_b32_e32 v213, 2, v87
	v_sub_u32_e32 v90, v87, v2
	s_nop 1
	v_min_u32_e32 v210, v212, v213
	global_load_dword v226, v210, s[100:101]
	v_add_u32_e32 v211, 256, v212
	v_min_u32_e32 v211, v211, v213
	global_load_dword v225, v211, s[100:101]
	v_add_u32_e32 v210, 512, v212
	v_min_u32_e32 v210, v210, v213
	global_load_dword v228, v210, s[100:101]
	v_add_u32_e32 v211, 768, v212
	v_min_u32_e32 v211, v211, v213
	global_load_dword v227, v211, s[100:101]
	v_add_u32_e32 v210, 1024, v212
	v_min_u32_e32 v210, v210, v213
	global_load_dword v230, v210, s[100:101]
	v_add_u32_e32 v211, 1280, v212
	v_min_u32_e32 v211, v211, v213
	global_load_dword v229, v211, s[100:101]
	v_add_u32_e32 v210, 1536, v212
	v_min_u32_e32 v210, v210, v213
	global_load_dword v232, v210, s[100:101]
	v_add_u32_e32 v211, 1792, v212
	v_min_u32_e32 v211, v211, v213
	global_load_dword v231, v211, s[100:101]
	v_add_u32_e32 v210, 2048, v212
	v_min_u32_e32 v210, v210, v213
	global_load_dword v234, v210, s[100:101]
	v_add_u32_e32 v211, 2304, v212
	v_min_u32_e32 v211, v211, v213
	global_load_dword v233, v211, s[100:101]
	v_add_u32_e32 v210, 2560, v212
	v_min_u32_e32 v210, v210, v213
	global_load_dword v236, v210, s[100:101]
	v_add_u32_e32 v211, 2816, v212
	v_min_u32_e32 v211, v211, v213
	global_load_dword v235, v211, s[100:101]
	v_add_u32_e32 v210, 3072, v212
	v_min_u32_e32 v210, v210, v213
	global_load_dword v238, v210, s[100:101]
	v_add_u32_e32 v211, 3328, v212
	v_min_u32_e32 v211, v211, v213
	global_load_dword v237, v211, s[100:101]
	v_add_u32_e32 v210, 3584, v212
	v_min_u32_e32 v210, v210, v213
	global_load_dword v239, v210, s[100:101]
	v_add_u32_e32 v211, 3840, v212
	v_min_u32_e32 v211, v211, v213
	global_load_dword v168, v211, s[100:101]
	v_add_u32_e32 v210, 4096, v212
	v_min_u32_e32 v210, v210, v213
	global_load_dword v114, v210, s[100:101]
	v_add_u32_e32 v211, 4352, v212
	v_min_u32_e32 v211, v211, v213
	global_load_dword v113, v211, s[100:101]
	v_add_u32_e32 v210, 4608, v212
	v_min_u32_e32 v210, v210, v213
	global_load_dword v116, v210, s[100:101]
	v_add_u32_e32 v211, 4864, v212
	v_min_u32_e32 v211, v211, v213
	global_load_dword v115, v211, s[100:101]
	v_add_u32_e32 v210, 5120, v212
	v_min_u32_e32 v210, v210, v213
	global_load_dword v118, v210, s[100:101]
	v_add_u32_e32 v211, 5376, v212
	v_min_u32_e32 v211, v211, v213
	global_load_dword v117, v211, s[100:101]
	v_add_u32_e32 v210, 5632, v212
	v_min_u32_e32 v210, v210, v213
	global_load_dword v120, v210, s[100:101]
	v_add_u32_e32 v211, 5888, v212
	v_min_u32_e32 v211, v211, v213
	global_load_dword v119, v211, s[100:101]
	v_add_u32_e32 v210, 6144, v212
	v_min_u32_e32 v210, v210, v213
	global_load_dword v122, v210, s[100:101]
	v_add_u32_e32 v211, 6400, v212
	v_min_u32_e32 v211, v211, v213
	global_load_dword v121, v211, s[100:101]
	v_add_u32_e32 v210, 6656, v212
	v_min_u32_e32 v210, v210, v213
	global_load_dword v124, v210, s[100:101]
	v_add_u32_e32 v211, 6912, v212
	v_min_u32_e32 v211, v211, v213
	global_load_dword v123, v211, s[100:101]
	v_add_u32_e32 v210, 7168, v212
	v_min_u32_e32 v210, v210, v213
	global_load_dword v126, v210, s[100:101]
	v_add_u32_e32 v211, 7424, v212
	v_min_u32_e32 v211, v211, v213
	global_load_dword v125, v211, s[100:101]
	v_add_u32_e32 v210, 7680, v212
	v_min_u32_e32 v210, v210, v213
	global_load_dword v128, v210, s[100:101]
	v_add_u32_e32 v211, 7936, v212
	v_min_u32_e32 v211, v211, v213
	global_load_dword v127, v211, s[100:101]
	v_add_u32_e32 v210, 8192, v212
	v_min_u32_e32 v210, v210, v213
	global_load_dword v130, v210, s[100:101]
	v_add_u32_e32 v211, 8448, v212
	v_min_u32_e32 v211, v211, v213
	global_load_dword v129, v211, s[100:101]
	v_add_u32_e32 v210, 8704, v212
	v_min_u32_e32 v210, v210, v213
	global_load_dword v132, v210, s[100:101]
	v_add_u32_e32 v211, 8960, v212
	v_min_u32_e32 v211, v211, v213
	global_load_dword v131, v211, s[100:101]
	v_add_u32_e32 v210, 9216, v212
	v_min_u32_e32 v210, v210, v213
	global_load_dword v134, v210, s[100:101]
	v_add_u32_e32 v211, 9472, v212
	v_min_u32_e32 v211, v211, v213
	global_load_dword v133, v211, s[100:101]
	v_add_u32_e32 v210, 9728, v212
	v_min_u32_e32 v210, v210, v213
	global_load_dword v136, v210, s[100:101]
	v_add_u32_e32 v211, 9984, v212
	v_min_u32_e32 v211, v211, v213
	global_load_dword v135, v211, s[100:101]
	v_add_u32_e32 v210, 10240, v212
	v_min_u32_e32 v210, v210, v213
	global_load_dword v138, v210, s[100:101]
	v_add_u32_e32 v211, 10496, v212
	v_min_u32_e32 v211, v211, v213
	global_load_dword v137, v211, s[100:101]
	v_add_u32_e32 v210, 10752, v212
	v_min_u32_e32 v210, v210, v213
	global_load_dword v140, v210, s[100:101]
	v_add_u32_e32 v211, 11008, v212
	v_min_u32_e32 v211, v211, v213
	global_load_dword v139, v211, s[100:101]
	v_add_u32_e32 v210, 11264, v212
	v_min_u32_e32 v210, v210, v213
	global_load_dword v142, v210, s[100:101]
	v_add_u32_e32 v211, 11520, v212
	v_min_u32_e32 v211, v211, v213
	global_load_dword v141, v211, s[100:101]
	v_add_u32_e32 v210, 11776, v212
	v_min_u32_e32 v210, v210, v213
	global_load_dword v144, v210, s[100:101]
	v_add_u32_e32 v211, 12032, v212
	v_min_u32_e32 v211, v211, v213
	global_load_dword v143, v211, s[100:101]
	v_add_u32_e32 v210, 12288, v212
	v_min_u32_e32 v210, v210, v213
	global_load_dword v146, v210, s[100:101]
	v_add_u32_e32 v211, 12544, v212
	v_min_u32_e32 v211, v211, v213
	global_load_dword v145, v211, s[100:101]
	v_add_u32_e32 v210, 12800, v212
	v_min_u32_e32 v210, v210, v213
	global_load_dword v148, v210, s[100:101]
	v_add_u32_e32 v211, 13056, v212
	v_min_u32_e32 v211, v211, v213
	global_load_dword v147, v211, s[100:101]
	v_add_u32_e32 v210, 13312, v212
	v_min_u32_e32 v210, v210, v213
	global_load_dword v150, v210, s[100:101]
	v_add_u32_e32 v211, 13568, v212
	v_min_u32_e32 v211, v211, v213
	global_load_dword v149, v211, s[100:101]
	v_add_u32_e32 v210, 13824, v212
	v_min_u32_e32 v210, v210, v213
	global_load_dword v152, v210, s[100:101]
	v_add_u32_e32 v211, 14080, v212
	v_min_u32_e32 v211, v211, v213
	global_load_dword v151, v211, s[100:101]
	v_add_u32_e32 v210, 14336, v212
	v_min_u32_e32 v210, v210, v213
	global_load_dword v155, v210, s[100:101]
	v_add_u32_e32 v211, 14592, v212
	v_min_u32_e32 v211, v211, v213
	global_load_dword v154, v211, s[100:101]
	v_add_u32_e32 v210, 14848, v212
	v_min_u32_e32 v210, v210, v213
	global_load_dword v157, v210, s[100:101]
	v_add_u32_e32 v211, 15104, v212
	v_min_u32_e32 v211, v211, v213
	global_load_dword v156, v211, s[100:101]
	v_add_u32_e32 v210, 15360, v212
	v_min_u32_e32 v210, v210, v213
	global_load_dword v159, v210, s[100:101]
	v_add_u32_e32 v211, 15616, v212
	v_min_u32_e32 v211, v211, v213
	global_load_dword v158, v211, s[100:101]
	v_add_u32_e32 v210, 15872, v212
	v_min_u32_e32 v210, v210, v213
	global_load_dword v161, v210, s[100:101]
	s_waitcnt vmcnt(47)
	s_movk_i32 s18, 0
	v_ashrrev_i32_e32 v91, 31, v226
	v_cmp_le_i32_e64 s[16:17], s18, v90
	v_or_b32_e32 v91, 0x80000000, v91
	v_xor_b32_e32 v91, v226, v91
	v_cndmask_b32_e64 v226, 0, v91, s[16:17]
	s_movk_i32 s18, 64
	v_ashrrev_i32_e32 v91, 31, v225
	v_cmp_le_i32_e64 s[16:17], s18, v90
	v_or_b32_e32 v91, 0x80000000, v91
	v_xor_b32_e32 v91, v225, v91
	v_cndmask_b32_e64 v225, 0, v91, s[16:17]
	s_movk_i32 s18, 128
	v_ashrrev_i32_e32 v91, 31, v228
	v_cmp_le_i32_e64 s[16:17], s18, v90
	v_or_b32_e32 v91, 0x80000000, v91
	v_xor_b32_e32 v91, v228, v91
	v_cndmask_b32_e64 v228, 0, v91, s[16:17]
	s_movk_i32 s18, 192
	v_ashrrev_i32_e32 v91, 31, v227
	v_cmp_le_i32_e64 s[16:17], s18, v90
	v_or_b32_e32 v91, 0x80000000, v91
	v_xor_b32_e32 v91, v227, v91
	v_cndmask_b32_e64 v227, 0, v91, s[16:17]
	s_movk_i32 s18, 256
	v_ashrrev_i32_e32 v91, 31, v230
	v_cmp_le_i32_e64 s[16:17], s18, v90
	v_or_b32_e32 v91, 0x80000000, v91
	v_xor_b32_e32 v91, v230, v91
	v_cndmask_b32_e64 v230, 0, v91, s[16:17]
	s_movk_i32 s18, 320
	v_ashrrev_i32_e32 v91, 31, v229
	v_cmp_le_i32_e64 s[16:17], s18, v90
	v_or_b32_e32 v91, 0x80000000, v91
	v_xor_b32_e32 v91, v229, v91
	v_cndmask_b32_e64 v229, 0, v91, s[16:17]
	s_movk_i32 s18, 384
	v_ashrrev_i32_e32 v91, 31, v232
	v_cmp_le_i32_e64 s[16:17], s18, v90
	v_or_b32_e32 v91, 0x80000000, v91
	v_xor_b32_e32 v91, v232, v91
	v_cndmask_b32_e64 v232, 0, v91, s[16:17]
	s_movk_i32 s18, 448
	v_ashrrev_i32_e32 v91, 31, v231
	v_cmp_le_i32_e64 s[16:17], s18, v90
	v_or_b32_e32 v91, 0x80000000, v91
	v_xor_b32_e32 v91, v231, v91
	v_cndmask_b32_e64 v231, 0, v91, s[16:17]
	s_movk_i32 s18, 512
	v_ashrrev_i32_e32 v91, 31, v234
	v_cmp_le_i32_e64 s[16:17], s18, v90
	v_or_b32_e32 v91, 0x80000000, v91
	v_xor_b32_e32 v91, v234, v91
	v_cndmask_b32_e64 v234, 0, v91, s[16:17]
	s_movk_i32 s18, 576
	v_ashrrev_i32_e32 v91, 31, v233
	v_cmp_le_i32_e64 s[16:17], s18, v90
	v_or_b32_e32 v91, 0x80000000, v91
	v_xor_b32_e32 v91, v233, v91
	v_cndmask_b32_e64 v233, 0, v91, s[16:17]
	s_movk_i32 s18, 640
	v_ashrrev_i32_e32 v91, 31, v236
	v_cmp_le_i32_e64 s[16:17], s18, v90
	v_or_b32_e32 v91, 0x80000000, v91
	v_xor_b32_e32 v91, v236, v91
	v_cndmask_b32_e64 v236, 0, v91, s[16:17]
	s_movk_i32 s18, 704
	v_ashrrev_i32_e32 v91, 31, v235
	v_cmp_le_i32_e64 s[16:17], s18, v90
	v_or_b32_e32 v91, 0x80000000, v91
	v_xor_b32_e32 v91, v235, v91
	v_cndmask_b32_e64 v235, 0, v91, s[16:17]
	s_movk_i32 s18, 768
	v_ashrrev_i32_e32 v91, 31, v238
	v_cmp_le_i32_e64 s[16:17], s18, v90
	v_or_b32_e32 v91, 0x80000000, v91
	v_xor_b32_e32 v91, v238, v91
	v_cndmask_b32_e64 v238, 0, v91, s[16:17]
	s_movk_i32 s18, 832
	v_ashrrev_i32_e32 v91, 31, v237
	v_cmp_le_i32_e64 s[16:17], s18, v90
	v_or_b32_e32 v91, 0x80000000, v91
	v_xor_b32_e32 v91, v237, v91
	v_cndmask_b32_e64 v237, 0, v91, s[16:17]
	s_movk_i32 s18, 896
	v_ashrrev_i32_e32 v91, 31, v239
	v_cmp_le_i32_e64 s[16:17], s18, v90
	v_or_b32_e32 v91, 0x80000000, v91
	v_xor_b32_e32 v91, v239, v91
	v_cndmask_b32_e64 v239, 0, v91, s[16:17]
	s_movk_i32 s18, 960
	v_ashrrev_i32_e32 v91, 31, v168
	v_cmp_le_i32_e64 s[16:17], s18, v90
	v_or_b32_e32 v91, 0x80000000, v91
	v_xor_b32_e32 v91, v168, v91
	v_cndmask_b32_e64 v168, 0, v91, s[16:17]
	ds_write2st64_b32 v6, v226, v225 offset0:144 offset1:145
	ds_write2st64_b32 v6, v228, v227 offset0:146 offset1:147
	ds_write2st64_b32 v6, v230, v229 offset0:148 offset1:149
	ds_write2st64_b32 v6, v232, v231 offset0:150 offset1:151
	ds_write2st64_b32 v6, v234, v233 offset0:152 offset1:153
	ds_write2st64_b32 v6, v236, v235 offset0:154 offset1:155
	ds_write2st64_b32 v6, v238, v237 offset0:156 offset1:157
	ds_write2st64_b32 v6, v239, v168 offset0:158 offset1:159
	v_add_u32_e32 v211, 16128, v212
	v_min_u32_e32 v211, v211, v213
	global_load_dword v160, v211, s[100:101]
	v_add_u32_e32 v210, 16384, v212
	v_min_u32_e32 v210, v210, v213
	global_load_dword v163, v210, s[100:101]
	v_add_u32_e32 v211, 16640, v212
	v_min_u32_e32 v211, v211, v213
	global_load_dword v162, v211, s[100:101]
	v_add_u32_e32 v210, 16896, v212
	v_min_u32_e32 v210, v210, v213
	global_load_dword v165, v210, s[100:101]
	v_add_u32_e32 v211, 17152, v212
	v_min_u32_e32 v211, v211, v213
	global_load_dword v164, v211, s[100:101]
	v_add_u32_e32 v210, 17408, v212
	v_min_u32_e32 v210, v210, v213
	global_load_dword v167, v210, s[100:101]
	v_add_u32_e32 v211, 17664, v212
	v_min_u32_e32 v211, v211, v213
	global_load_dword v166, v211, s[100:101]
	v_add_u32_e32 v210, 17920, v212
	v_min_u32_e32 v210, v210, v213
	global_load_dword v170, v210, s[100:101]
	v_add_u32_e32 v211, 18176, v212
	v_min_u32_e32 v211, v211, v213
	global_load_dword v169, v211, s[100:101]
	v_add_u32_e32 v210, 18432, v212
	v_min_u32_e32 v210, v210, v213
	global_load_dword v172, v210, s[100:101]
	v_add_u32_e32 v211, 18688, v212
	v_min_u32_e32 v211, v211, v213
	global_load_dword v171, v211, s[100:101]
	v_add_u32_e32 v210, 18944, v212
	v_min_u32_e32 v210, v210, v213
	global_load_dword v174, v210, s[100:101]
	v_add_u32_e32 v211, 19200, v212
	v_min_u32_e32 v211, v211, v213
	global_load_dword v173, v211, s[100:101]
	v_add_u32_e32 v210, 19456, v212
	v_min_u32_e32 v210, v210, v213
	global_load_dword v176, v210, s[100:101]
	v_add_u32_e32 v211, 19712, v212
	v_min_u32_e32 v211, v211, v213
	global_load_dword v175, v211, s[100:101]
	v_add_u32_e32 v210, 19968, v212
	v_min_u32_e32 v210, v210, v213
	global_load_dword v178, v210, s[100:101]
	s_waitcnt vmcnt(47)
	v_add_u32_e32 v211, 20224, v212
	v_min_u32_e32 v211, v211, v213
	global_load_dword v177, v211, s[100:101]
	v_add_u32_e32 v210, 20480, v212
	v_min_u32_e32 v210, v210, v213
	global_load_dword v180, v210, s[100:101]
	v_add_u32_e32 v211, 20736, v212
	v_min_u32_e32 v211, v211, v213
	global_load_dword v179, v211, s[100:101]
	v_add_u32_e32 v210, 20992, v212
	v_min_u32_e32 v210, v210, v213
	global_load_dword v182, v210, s[100:101]
	v_add_u32_e32 v211, 21248, v212
	v_min_u32_e32 v211, v211, v213
	global_load_dword v181, v211, s[100:101]
	v_add_u32_e32 v210, 21504, v212
	v_min_u32_e32 v210, v210, v213
	global_load_dword v184, v210, s[100:101]
	v_add_u32_e32 v211, 21760, v212
	v_min_u32_e32 v211, v211, v213
	global_load_dword v183, v211, s[100:101]
	v_add_u32_e32 v210, 22016, v212
	v_min_u32_e32 v210, v210, v213
	global_load_dword v186, v210, s[100:101]
	v_add_u32_e32 v211, 22272, v212
	v_min_u32_e32 v211, v211, v213
	global_load_dword v185, v211, s[100:101]
	v_add_u32_e32 v210, 22528, v212
	v_min_u32_e32 v210, v210, v213
	global_load_dword v188, v210, s[100:101]
	v_add_u32_e32 v211, 22784, v212
	v_min_u32_e32 v211, v211, v213
	global_load_dword v187, v211, s[100:101]
	v_add_u32_e32 v210, 23040, v212
	v_min_u32_e32 v210, v210, v213
	global_load_dword v190, v210, s[100:101]
	v_add_u32_e32 v211, 23296, v212
	v_min_u32_e32 v211, v211, v213
	global_load_dword v189, v211, s[100:101]
	v_add_u32_e32 v210, 23552, v212
	v_min_u32_e32 v210, v210, v213
	global_load_dword v192, v210, s[100:101]
	v_add_u32_e32 v211, 23808, v212
	v_min_u32_e32 v211, v211, v213
	global_load_dword v191, v211, s[100:101]
	v_add_u32_e32 v210, 24064, v212
	v_min_u32_e32 v210, v210, v213
	global_load_dword v194, v210, s[100:101]
	s_waitcnt vmcnt(47)
	v_add_u32_e32 v211, 24320, v212
	v_min_u32_e32 v211, v211, v213
	global_load_dword v193, v211, s[100:101]
	v_add_u32_e32 v210, 24576, v212
	v_min_u32_e32 v210, v210, v213
	global_load_dword v196, v210, s[100:101]
	v_add_u32_e32 v211, 24832, v212
	v_min_u32_e32 v211, v211, v213
	global_load_dword v195, v211, s[100:101]
	v_add_u32_e32 v210, 25088, v212
	v_min_u32_e32 v210, v210, v213
	global_load_dword v198, v210, s[100:101]
	v_add_u32_e32 v211, 25344, v212
	v_min_u32_e32 v211, v211, v213
	global_load_dword v197, v211, s[100:101]
	v_add_u32_e32 v210, 25600, v212
	v_min_u32_e32 v210, v210, v213
	global_load_dword v200, v210, s[100:101]
	v_add_u32_e32 v211, 25856, v212
	v_min_u32_e32 v211, v211, v213
	global_load_dword v199, v211, s[100:101]
	v_add_u32_e32 v210, 26112, v212
	v_min_u32_e32 v210, v210, v213
	global_load_dword v202, v210, s[100:101]
	v_add_u32_e32 v211, 26368, v212
	v_min_u32_e32 v211, v211, v213
	global_load_dword v201, v211, s[100:101]
	v_add_u32_e32 v210, 26624, v212
	v_min_u32_e32 v210, v210, v213
	global_load_dword v204, v210, s[100:101]
	v_add_u32_e32 v211, 26880, v212
	v_min_u32_e32 v211, v211, v213
	global_load_dword v203, v211, s[100:101]
	v_add_u32_e32 v210, 27136, v212
	v_min_u32_e32 v210, v210, v213
	global_load_dword v206, v210, s[100:101]
	v_add_u32_e32 v211, 27392, v212
	v_min_u32_e32 v211, v211, v213
	global_load_dword v205, v211, s[100:101]
	v_add_u32_e32 v210, 27648, v212
	v_min_u32_e32 v210, v210, v213
	global_load_dword v222, v210, s[100:101]
	v_add_u32_e32 v211, 27904, v212
	v_min_u32_e32 v211, v211, v213
	global_load_dword v207, v211, s[100:101]
	v_add_u32_e32 v210, 28160, v212
	v_min_u32_e32 v210, v210, v213
	global_load_dword v224, v210, s[100:101]
	s_waitcnt vmcnt(47)
	v_add_u32_e32 v211, 28416, v212
	v_min_u32_e32 v211, v211, v213
	global_load_dword v223, v211, s[100:101]
	v_add_u32_e32 v210, 28672, v212
	v_min_u32_e32 v210, v210, v213
	global_load_dword v226, v210, s[100:101]
	v_add_u32_e32 v211, 28928, v212
	v_min_u32_e32 v211, v211, v213
	global_load_dword v225, v211, s[100:101]
	v_add_u32_e32 v210, 29184, v212
	v_min_u32_e32 v210, v210, v213
	global_load_dword v228, v210, s[100:101]
	v_add_u32_e32 v211, 29440, v212
	v_min_u32_e32 v211, v211, v213
	global_load_dword v227, v211, s[100:101]
	v_add_u32_e32 v210, 29696, v212
	v_min_u32_e32 v210, v210, v213
	global_load_dword v230, v210, s[100:101]
	v_add_u32_e32 v211, 29952, v212
	v_min_u32_e32 v211, v211, v213
	global_load_dword v229, v211, s[100:101]
	v_add_u32_e32 v210, 30208, v212
	v_min_u32_e32 v210, v210, v213
	global_load_dword v232, v210, s[100:101]
	v_add_u32_e32 v211, 30464, v212
	v_min_u32_e32 v211, v211, v213
	global_load_dword v231, v211, s[100:101]
	v_add_u32_e32 v210, 30720, v212
	v_min_u32_e32 v210, v210, v213
	global_load_dword v234, v210, s[100:101]
	v_add_u32_e32 v211, 30976, v212
	v_min_u32_e32 v211, v211, v213
	global_load_dword v233, v211, s[100:101]
	v_add_u32_e32 v210, 31232, v212
	v_min_u32_e32 v210, v210, v213
	global_load_dword v236, v210, s[100:101]
	v_add_u32_e32 v211, 31488, v212
	v_min_u32_e32 v211, v211, v213
	global_load_dword v235, v211, s[100:101]
	v_add_u32_e32 v210, 31744, v212
	v_min_u32_e32 v210, v210, v213
	global_load_dword v238, v210, s[100:101]
	v_add_u32_e32 v211, 32000, v212
	v_min_u32_e32 v211, v211, v213
	global_load_dword v237, v211, s[100:101]
	v_add_u32_e32 v210, 32256, v212
	v_min_u32_e32 v210, v210, v213
	global_load_dword v239, v210, s[100:101]
	s_waitcnt vmcnt(47)
	v_add_u32_e32 v211, 32512, v212
	v_min_u32_e32 v211, v211, v213
	global_load_dword v168, v211, s[100:101]
	s_waitcnt vmcnt(63)
	s_movk_i32 s18, 1024
	v_ashrrev_i32_e32 v91, 31, v114
	v_cmp_le_i32_e64 s[16:17], s18, v90
	v_or_b32_e32 v91, 0x80000000, v91
	v_xor_b32_e32 v91, v114, v91
	v_cndmask_b32_e64 v114, 0, v91, s[16:17]
	s_movk_i32 s18, 1088
	v_ashrrev_i32_e32 v91, 31, v113
	v_cmp_le_i32_e64 s[16:17], s18, v90
	v_or_b32_e32 v91, 0x80000000, v91
	v_xor_b32_e32 v91, v113, v91
	v_cndmask_b32_e64 v113, 0, v91, s[16:17]
	s_movk_i32 s18, 1152
	v_ashrrev_i32_e32 v91, 31, v116
	v_cmp_le_i32_e64 s[16:17], s18, v90
	v_or_b32_e32 v91, 0x80000000, v91
	v_xor_b32_e32 v91, v116, v91
	v_cndmask_b32_e64 v116, 0, v91, s[16:17]
	s_movk_i32 s18, 1216
	v_ashrrev_i32_e32 v91, 31, v115
	v_cmp_le_i32_e64 s[16:17], s18, v90
	v_or_b32_e32 v91, 0x80000000, v91
	v_xor_b32_e32 v91, v115, v91
	v_cndmask_b32_e64 v115, 0, v91, s[16:17]
	s_movk_i32 s18, 1280
	v_ashrrev_i32_e32 v91, 31, v118
	v_cmp_le_i32_e64 s[16:17], s18, v90
	v_or_b32_e32 v91, 0x80000000, v91
	v_xor_b32_e32 v91, v118, v91
	v_cndmask_b32_e64 v118, 0, v91, s[16:17]
	s_movk_i32 s18, 1344
	v_ashrrev_i32_e32 v91, 31, v117
	v_cmp_le_i32_e64 s[16:17], s18, v90
	v_or_b32_e32 v91, 0x80000000, v91
	v_xor_b32_e32 v91, v117, v91
	v_cndmask_b32_e64 v117, 0, v91, s[16:17]
	s_movk_i32 s18, 1408
	v_ashrrev_i32_e32 v91, 31, v120
	v_cmp_le_i32_e64 s[16:17], s18, v90
	v_or_b32_e32 v91, 0x80000000, v91
	v_xor_b32_e32 v91, v120, v91
	v_cndmask_b32_e64 v120, 0, v91, s[16:17]
	s_movk_i32 s18, 1472
	v_ashrrev_i32_e32 v91, 31, v119
	v_cmp_le_i32_e64 s[16:17], s18, v90
	v_or_b32_e32 v91, 0x80000000, v91
	v_xor_b32_e32 v91, v119, v91
	v_cndmask_b32_e64 v119, 0, v91, s[16:17]
	s_waitcnt vmcnt(63)
	s_movk_i32 s18, 1536
	v_ashrrev_i32_e32 v91, 31, v122
	v_cmp_le_i32_e64 s[16:17], s18, v90
	v_or_b32_e32 v91, 0x80000000, v91
	v_xor_b32_e32 v91, v122, v91
	v_cndmask_b32_e64 v122, 0, v91, s[16:17]
	s_movk_i32 s18, 1600
	v_ashrrev_i32_e32 v91, 31, v121
	v_cmp_le_i32_e64 s[16:17], s18, v90
	v_or_b32_e32 v91, 0x80000000, v91
	v_xor_b32_e32 v91, v121, v91
	v_cndmask_b32_e64 v121, 0, v91, s[16:17]
	s_movk_i32 s18, 1664
	v_ashrrev_i32_e32 v91, 31, v124
	v_cmp_le_i32_e64 s[16:17], s18, v90
	v_or_b32_e32 v91, 0x80000000, v91
	v_xor_b32_e32 v91, v124, v91
	v_cndmask_b32_e64 v124, 0, v91, s[16:17]
	s_movk_i32 s18, 1728
	v_ashrrev_i32_e32 v91, 31, v123
	v_cmp_le_i32_e64 s[16:17], s18, v90
	v_or_b32_e32 v91, 0x80000000, v91
	v_xor_b32_e32 v91, v123, v91
	v_cndmask_b32_e64 v123, 0, v91, s[16:17]
	s_movk_i32 s18, 1792
	v_ashrrev_i32_e32 v91, 31, v126
	v_cmp_le_i32_e64 s[16:17], s18, v90
	v_or_b32_e32 v91, 0x80000000, v91
	v_xor_b32_e32 v91, v126, v91
	v_cndmask_b32_e64 v126, 0, v91, s[16:17]
	s_movk_i32 s18, 1856
	v_ashrrev_i32_e32 v91, 31, v125
	v_cmp_le_i32_e64 s[16:17], s18, v90
	v_or_b32_e32 v91, 0x80000000, v91
	v_xor_b32_e32 v91, v125, v91
	v_cndmask_b32_e64 v125, 0, v91, s[16:17]
	s_movk_i32 s18, 1920
	v_ashrrev_i32_e32 v91, 31, v128
	v_cmp_le_i32_e64 s[16:17], s18, v90
	v_or_b32_e32 v91, 0x80000000, v91
	v_xor_b32_e32 v91, v128, v91
	v_cndmask_b32_e64 v128, 0, v91, s[16:17]
	s_movk_i32 s18, 1984
	v_ashrrev_i32_e32 v91, 31, v127
	v_cmp_le_i32_e64 s[16:17], s18, v90
	v_or_b32_e32 v91, 0x80000000, v91
	v_xor_b32_e32 v91, v127, v91
	v_cndmask_b32_e64 v127, 0, v91, s[16:17]
	s_waitcnt vmcnt(63)
	s_movk_i32 s18, 2048
	v_ashrrev_i32_e32 v91, 31, v130
	v_cmp_le_i32_e64 s[16:17], s18, v90
	v_or_b32_e32 v91, 0x80000000, v91
	v_xor_b32_e32 v91, v130, v91
	v_cndmask_b32_e64 v130, 0, v91, s[16:17]
	s_movk_i32 s18, 2112
	v_ashrrev_i32_e32 v91, 31, v129
	v_cmp_le_i32_e64 s[16:17], s18, v90
	v_or_b32_e32 v91, 0x80000000, v91
	v_xor_b32_e32 v91, v129, v91
	v_cndmask_b32_e64 v129, 0, v91, s[16:17]
	s_movk_i32 s18, 2176
	v_ashrrev_i32_e32 v91, 31, v132
	v_cmp_le_i32_e64 s[16:17], s18, v90
	v_or_b32_e32 v91, 0x80000000, v91
	v_xor_b32_e32 v91, v132, v91
	v_cndmask_b32_e64 v132, 0, v91, s[16:17]
	s_movk_i32 s18, 2240
	v_ashrrev_i32_e32 v91, 31, v131
	v_cmp_le_i32_e64 s[16:17], s18, v90
	v_or_b32_e32 v91, 0x80000000, v91
	v_xor_b32_e32 v91, v131, v91
	v_cndmask_b32_e64 v131, 0, v91, s[16:17]
	s_movk_i32 s18, 2304
	v_ashrrev_i32_e32 v91, 31, v134
	v_cmp_le_i32_e64 s[16:17], s18, v90
	v_or_b32_e32 v91, 0x80000000, v91
	v_xor_b32_e32 v91, v134, v91
	v_cndmask_b32_e64 v134, 0, v91, s[16:17]
	s_movk_i32 s18, 2368
	v_ashrrev_i32_e32 v91, 31, v133
	v_cmp_le_i32_e64 s[16:17], s18, v90
	v_or_b32_e32 v91, 0x80000000, v91
	v_xor_b32_e32 v91, v133, v91
	v_cndmask_b32_e64 v133, 0, v91, s[16:17]
	s_movk_i32 s18, 2432
	v_ashrrev_i32_e32 v91, 31, v136
	v_cmp_le_i32_e64 s[16:17], s18, v90
	v_or_b32_e32 v91, 0x80000000, v91
	v_xor_b32_e32 v91, v136, v91
	v_cndmask_b32_e64 v136, 0, v91, s[16:17]
	s_movk_i32 s18, 2496
	v_ashrrev_i32_e32 v91, 31, v135
	v_cmp_le_i32_e64 s[16:17], s18, v90
	v_or_b32_e32 v91, 0x80000000, v91
	v_xor_b32_e32 v91, v135, v91
	v_cndmask_b32_e64 v135, 0, v91, s[16:17]
	s_waitcnt vmcnt(63)
	s_movk_i32 s18, 2560
	v_ashrrev_i32_e32 v91, 31, v138
	v_cmp_le_i32_e64 s[16:17], s18, v90
	v_or_b32_e32 v91, 0x80000000, v91
	v_xor_b32_e32 v91, v138, v91
	v_cndmask_b32_e64 v138, 0, v91, s[16:17]
	s_movk_i32 s18, 2624
	v_ashrrev_i32_e32 v91, 31, v137
	v_cmp_le_i32_e64 s[16:17], s18, v90
	v_or_b32_e32 v91, 0x80000000, v91
	v_xor_b32_e32 v91, v137, v91
	v_cndmask_b32_e64 v137, 0, v91, s[16:17]
	s_movk_i32 s18, 2688
	v_ashrrev_i32_e32 v91, 31, v140
	v_cmp_le_i32_e64 s[16:17], s18, v90
	v_or_b32_e32 v91, 0x80000000, v91
	v_xor_b32_e32 v91, v140, v91
	v_cndmask_b32_e64 v140, 0, v91, s[16:17]
	s_movk_i32 s18, 2752
	v_ashrrev_i32_e32 v91, 31, v139
	v_cmp_le_i32_e64 s[16:17], s18, v90
	v_or_b32_e32 v91, 0x80000000, v91
	v_xor_b32_e32 v91, v139, v91
	v_cndmask_b32_e64 v139, 0, v91, s[16:17]
	s_movk_i32 s18, 2816
	v_ashrrev_i32_e32 v91, 31, v142
	v_cmp_le_i32_e64 s[16:17], s18, v90
	v_or_b32_e32 v91, 0x80000000, v91
	v_xor_b32_e32 v91, v142, v91
	v_cndmask_b32_e64 v142, 0, v91, s[16:17]
	s_movk_i32 s18, 2880
	v_ashrrev_i32_e32 v91, 31, v141
	v_cmp_le_i32_e64 s[16:17], s18, v90
	v_or_b32_e32 v91, 0x80000000, v91
	v_xor_b32_e32 v91, v141, v91
	v_cndmask_b32_e64 v141, 0, v91, s[16:17]
	s_movk_i32 s18, 2944
	v_ashrrev_i32_e32 v91, 31, v144
	v_cmp_le_i32_e64 s[16:17], s18, v90
	v_or_b32_e32 v91, 0x80000000, v91
	v_xor_b32_e32 v91, v144, v91
	v_cndmask_b32_e64 v144, 0, v91, s[16:17]
	s_movk_i32 s18, 3008
	v_ashrrev_i32_e32 v91, 31, v143
	v_cmp_le_i32_e64 s[16:17], s18, v90
	v_or_b32_e32 v91, 0x80000000, v91
	v_xor_b32_e32 v91, v143, v91
	v_cndmask_b32_e64 v143, 0, v91, s[16:17]
	s_waitcnt vmcnt(63)
	s_movk_i32 s18, 3072
	v_ashrrev_i32_e32 v91, 31, v146
	v_cmp_le_i32_e64 s[16:17], s18, v90
	v_or_b32_e32 v91, 0x80000000, v91
	v_xor_b32_e32 v91, v146, v91
	v_cndmask_b32_e64 v146, 0, v91, s[16:17]
	s_movk_i32 s18, 3136
	v_ashrrev_i32_e32 v91, 31, v145
	v_cmp_le_i32_e64 s[16:17], s18, v90
	v_or_b32_e32 v91, 0x80000000, v91
	v_xor_b32_e32 v91, v145, v91
	v_cndmask_b32_e64 v145, 0, v91, s[16:17]
	s_movk_i32 s18, 3200
	v_ashrrev_i32_e32 v91, 31, v148
	v_cmp_le_i32_e64 s[16:17], s18, v90
	v_or_b32_e32 v91, 0x80000000, v91
	v_xor_b32_e32 v91, v148, v91
	v_cndmask_b32_e64 v148, 0, v91, s[16:17]
	s_movk_i32 s18, 3264
	v_ashrrev_i32_e32 v91, 31, v147
	v_cmp_le_i32_e64 s[16:17], s18, v90
	v_or_b32_e32 v91, 0x80000000, v91
	v_xor_b32_e32 v91, v147, v91
	v_cndmask_b32_e64 v147, 0, v91, s[16:17]
	s_movk_i32 s18, 3328
	v_ashrrev_i32_e32 v91, 31, v150
	v_cmp_le_i32_e64 s[16:17], s18, v90
	v_or_b32_e32 v91, 0x80000000, v91
	v_xor_b32_e32 v91, v150, v91
	v_cndmask_b32_e64 v150, 0, v91, s[16:17]
	s_movk_i32 s18, 3392
	v_ashrrev_i32_e32 v91, 31, v149
	v_cmp_le_i32_e64 s[16:17], s18, v90
	v_or_b32_e32 v91, 0x80000000, v91
	v_xor_b32_e32 v91, v149, v91
	v_cndmask_b32_e64 v149, 0, v91, s[16:17]
	s_movk_i32 s18, 3456
	v_ashrrev_i32_e32 v91, 31, v152
	v_cmp_le_i32_e64 s[16:17], s18, v90
	v_or_b32_e32 v91, 0x80000000, v91
	v_xor_b32_e32 v91, v152, v91
	v_cndmask_b32_e64 v152, 0, v91, s[16:17]
	s_movk_i32 s18, 3520
	v_ashrrev_i32_e32 v91, 31, v151
	v_cmp_le_i32_e64 s[16:17], s18, v90
	v_or_b32_e32 v91, 0x80000000, v91
	v_xor_b32_e32 v91, v151, v91
	v_cndmask_b32_e64 v151, 0, v91, s[16:17]
	s_waitcnt vmcnt(63)
	s_movk_i32 s18, 3584
	v_ashrrev_i32_e32 v91, 31, v155
	v_cmp_le_i32_e64 s[16:17], s18, v90
	v_or_b32_e32 v91, 0x80000000, v91
	v_xor_b32_e32 v91, v155, v91
	v_cndmask_b32_e64 v155, 0, v91, s[16:17]
	s_movk_i32 s18, 3648
	v_ashrrev_i32_e32 v91, 31, v154
	v_cmp_le_i32_e64 s[16:17], s18, v90
	v_or_b32_e32 v91, 0x80000000, v91
	v_xor_b32_e32 v91, v154, v91
	v_cndmask_b32_e64 v154, 0, v91, s[16:17]
	s_movk_i32 s18, 3712
	v_ashrrev_i32_e32 v91, 31, v157
	v_cmp_le_i32_e64 s[16:17], s18, v90
	v_or_b32_e32 v91, 0x80000000, v91
	v_xor_b32_e32 v91, v157, v91
	v_cndmask_b32_e64 v157, 0, v91, s[16:17]
	s_movk_i32 s18, 3776
	v_ashrrev_i32_e32 v91, 31, v156
	v_cmp_le_i32_e64 s[16:17], s18, v90
	v_or_b32_e32 v91, 0x80000000, v91
	v_xor_b32_e32 v91, v156, v91
	v_cndmask_b32_e64 v156, 0, v91, s[16:17]
	s_movk_i32 s18, 3840
	v_ashrrev_i32_e32 v91, 31, v159
	v_cmp_le_i32_e64 s[16:17], s18, v90
	v_or_b32_e32 v91, 0x80000000, v91
	v_xor_b32_e32 v91, v159, v91
	v_cndmask_b32_e64 v159, 0, v91, s[16:17]
	s_movk_i32 s18, 3904
	v_ashrrev_i32_e32 v91, 31, v158
	v_cmp_le_i32_e64 s[16:17], s18, v90
	v_or_b32_e32 v91, 0x80000000, v91
	v_xor_b32_e32 v91, v158, v91
	v_cndmask_b32_e64 v158, 0, v91, s[16:17]
	s_movk_i32 s18, 3968
	v_ashrrev_i32_e32 v91, 31, v161
	v_cmp_le_i32_e64 s[16:17], s18, v90
	v_or_b32_e32 v91, 0x80000000, v91
	v_xor_b32_e32 v91, v161, v91
	v_cndmask_b32_e64 v161, 0, v91, s[16:17]
	s_movk_i32 s18, 4032
	v_ashrrev_i32_e32 v91, 31, v160
	v_cmp_le_i32_e64 s[16:17], s18, v90
	v_or_b32_e32 v91, 0x80000000, v91
	v_xor_b32_e32 v91, v160, v91
	v_cndmask_b32_e64 v160, 0, v91, s[16:17]
	s_waitcnt vmcnt(56)
	s_movk_i32 s18, 4096
	v_ashrrev_i32_e32 v91, 31, v163
	v_cmp_le_i32_e64 s[16:17], s18, v90
	v_or_b32_e32 v91, 0x80000000, v91
	v_xor_b32_e32 v91, v163, v91
	v_cndmask_b32_e64 v163, 0, v91, s[16:17]
	s_movk_i32 s18, 4160
	v_ashrrev_i32_e32 v91, 31, v162
	v_cmp_le_i32_e64 s[16:17], s18, v90
	v_or_b32_e32 v91, 0x80000000, v91
	v_xor_b32_e32 v91, v162, v91
	v_cndmask_b32_e64 v162, 0, v91, s[16:17]
	s_movk_i32 s18, 4224
	v_ashrrev_i32_e32 v91, 31, v165
	v_cmp_le_i32_e64 s[16:17], s18, v90
	v_or_b32_e32 v91, 0x80000000, v91
	v_xor_b32_e32 v91, v165, v91
	v_cndmask_b32_e64 v165, 0, v91, s[16:17]
	s_movk_i32 s18, 4288
	v_ashrrev_i32_e32 v91, 31, v164
	v_cmp_le_i32_e64 s[16:17], s18, v90
	v_or_b32_e32 v91, 0x80000000, v91
	v_xor_b32_e32 v91, v164, v91
	v_cndmask_b32_e64 v164, 0, v91, s[16:17]
	s_movk_i32 s18, 4352
	v_ashrrev_i32_e32 v91, 31, v167
	v_cmp_le_i32_e64 s[16:17], s18, v90
	v_or_b32_e32 v91, 0x80000000, v91
	v_xor_b32_e32 v91, v167, v91
	v_cndmask_b32_e64 v167, 0, v91, s[16:17]
	s_movk_i32 s18, 4416
	v_ashrrev_i32_e32 v91, 31, v166
	v_cmp_le_i32_e64 s[16:17], s18, v90
	v_or_b32_e32 v91, 0x80000000, v91
	v_xor_b32_e32 v91, v166, v91
	v_cndmask_b32_e64 v166, 0, v91, s[16:17]
	s_movk_i32 s18, 4480
	v_ashrrev_i32_e32 v91, 31, v170
	v_cmp_le_i32_e64 s[16:17], s18, v90
	v_or_b32_e32 v91, 0x80000000, v91
	v_xor_b32_e32 v91, v170, v91
	v_cndmask_b32_e64 v170, 0, v91, s[16:17]
	s_movk_i32 s18, 4544
	v_ashrrev_i32_e32 v91, 31, v169
	v_cmp_le_i32_e64 s[16:17], s18, v90
	v_or_b32_e32 v91, 0x80000000, v91
	v_xor_b32_e32 v91, v169, v91
	v_cndmask_b32_e64 v169, 0, v91, s[16:17]
	s_waitcnt vmcnt(48)
	s_movk_i32 s18, 4608
	v_ashrrev_i32_e32 v91, 31, v172
	v_cmp_le_i32_e64 s[16:17], s18, v90
	v_or_b32_e32 v91, 0x80000000, v91
	v_xor_b32_e32 v91, v172, v91
	v_cndmask_b32_e64 v172, 0, v91, s[16:17]
	s_movk_i32 s18, 4672
	v_ashrrev_i32_e32 v91, 31, v171
	v_cmp_le_i32_e64 s[16:17], s18, v90
	v_or_b32_e32 v91, 0x80000000, v91
	v_xor_b32_e32 v91, v171, v91
	v_cndmask_b32_e64 v171, 0, v91, s[16:17]
	s_movk_i32 s18, 4736
	v_ashrrev_i32_e32 v91, 31, v174
	v_cmp_le_i32_e64 s[16:17], s18, v90
	v_or_b32_e32 v91, 0x80000000, v91
	v_xor_b32_e32 v91, v174, v91
	v_cndmask_b32_e64 v174, 0, v91, s[16:17]
	s_movk_i32 s18, 4800
	v_ashrrev_i32_e32 v91, 31, v173
	v_cmp_le_i32_e64 s[16:17], s18, v90
	v_or_b32_e32 v91, 0x80000000, v91
	v_xor_b32_e32 v91, v173, v91
	v_cndmask_b32_e64 v173, 0, v91, s[16:17]
	s_movk_i32 s18, 4864
	v_ashrrev_i32_e32 v91, 31, v176
	v_cmp_le_i32_e64 s[16:17], s18, v90
	v_or_b32_e32 v91, 0x80000000, v91
	v_xor_b32_e32 v91, v176, v91
	v_cndmask_b32_e64 v176, 0, v91, s[16:17]
	s_movk_i32 s18, 4928
	v_ashrrev_i32_e32 v91, 31, v175
	v_cmp_le_i32_e64 s[16:17], s18, v90
	v_or_b32_e32 v91, 0x80000000, v91
	v_xor_b32_e32 v91, v175, v91
	v_cndmask_b32_e64 v175, 0, v91, s[16:17]
	s_movk_i32 s18, 4992
	v_ashrrev_i32_e32 v91, 31, v178
	v_cmp_le_i32_e64 s[16:17], s18, v90
	v_or_b32_e32 v91, 0x80000000, v91
	v_xor_b32_e32 v91, v178, v91
	v_cndmask_b32_e64 v178, 0, v91, s[16:17]
	s_movk_i32 s18, 5056
	v_ashrrev_i32_e32 v91, 31, v177
	v_cmp_le_i32_e64 s[16:17], s18, v90
	v_or_b32_e32 v91, 0x80000000, v91
	v_xor_b32_e32 v91, v177, v91
	v_cndmask_b32_e64 v177, 0, v91, s[16:17]
	s_waitcnt vmcnt(40)
	s_movk_i32 s18, 5120
	v_ashrrev_i32_e32 v91, 31, v180
	v_cmp_le_i32_e64 s[16:17], s18, v90
	v_or_b32_e32 v91, 0x80000000, v91
	v_xor_b32_e32 v91, v180, v91
	v_cndmask_b32_e64 v180, 0, v91, s[16:17]
	s_movk_i32 s18, 5184
	v_ashrrev_i32_e32 v91, 31, v179
	v_cmp_le_i32_e64 s[16:17], s18, v90
	v_or_b32_e32 v91, 0x80000000, v91
	v_xor_b32_e32 v91, v179, v91
	v_cndmask_b32_e64 v179, 0, v91, s[16:17]
	s_movk_i32 s18, 5248
	v_ashrrev_i32_e32 v91, 31, v182
	v_cmp_le_i32_e64 s[16:17], s18, v90
	v_or_b32_e32 v91, 0x80000000, v91
	v_xor_b32_e32 v91, v182, v91
	v_cndmask_b32_e64 v182, 0, v91, s[16:17]
	s_movk_i32 s18, 5312
	v_ashrrev_i32_e32 v91, 31, v181
	v_cmp_le_i32_e64 s[16:17], s18, v90
	v_or_b32_e32 v91, 0x80000000, v91
	v_xor_b32_e32 v91, v181, v91
	v_cndmask_b32_e64 v181, 0, v91, s[16:17]
	s_movk_i32 s18, 5376
	v_ashrrev_i32_e32 v91, 31, v184
	v_cmp_le_i32_e64 s[16:17], s18, v90
	v_or_b32_e32 v91, 0x80000000, v91
	v_xor_b32_e32 v91, v184, v91
	v_cndmask_b32_e64 v184, 0, v91, s[16:17]
	s_movk_i32 s18, 5440
	v_ashrrev_i32_e32 v91, 31, v183
	v_cmp_le_i32_e64 s[16:17], s18, v90
	v_or_b32_e32 v91, 0x80000000, v91
	v_xor_b32_e32 v91, v183, v91
	v_cndmask_b32_e64 v183, 0, v91, s[16:17]
	s_movk_i32 s18, 5504
	v_ashrrev_i32_e32 v91, 31, v186
	v_cmp_le_i32_e64 s[16:17], s18, v90
	v_or_b32_e32 v91, 0x80000000, v91
	v_xor_b32_e32 v91, v186, v91
	v_cndmask_b32_e64 v186, 0, v91, s[16:17]
	s_movk_i32 s18, 5568
	v_ashrrev_i32_e32 v91, 31, v185
	v_cmp_le_i32_e64 s[16:17], s18, v90
	v_or_b32_e32 v91, 0x80000000, v91
	v_xor_b32_e32 v91, v185, v91
	v_cndmask_b32_e64 v185, 0, v91, s[16:17]
	s_waitcnt vmcnt(32)
	s_movk_i32 s18, 5632
	v_ashrrev_i32_e32 v91, 31, v188
	v_cmp_le_i32_e64 s[16:17], s18, v90
	v_or_b32_e32 v91, 0x80000000, v91
	v_xor_b32_e32 v91, v188, v91
	v_cndmask_b32_e64 v188, 0, v91, s[16:17]
	s_movk_i32 s18, 5696
	v_ashrrev_i32_e32 v91, 31, v187
	v_cmp_le_i32_e64 s[16:17], s18, v90
	v_or_b32_e32 v91, 0x80000000, v91
	v_xor_b32_e32 v91, v187, v91
	v_cndmask_b32_e64 v187, 0, v91, s[16:17]
	s_movk_i32 s18, 5760
	v_ashrrev_i32_e32 v91, 31, v190
	v_cmp_le_i32_e64 s[16:17], s18, v90
	v_or_b32_e32 v91, 0x80000000, v91
	v_xor_b32_e32 v91, v190, v91
	v_cndmask_b32_e64 v190, 0, v91, s[16:17]
	s_movk_i32 s18, 5824
	v_ashrrev_i32_e32 v91, 31, v189
	v_cmp_le_i32_e64 s[16:17], s18, v90
	v_or_b32_e32 v91, 0x80000000, v91
	v_xor_b32_e32 v91, v189, v91
	v_cndmask_b32_e64 v189, 0, v91, s[16:17]
	s_movk_i32 s18, 5888
	v_ashrrev_i32_e32 v91, 31, v192
	v_cmp_le_i32_e64 s[16:17], s18, v90
	v_or_b32_e32 v91, 0x80000000, v91
	v_xor_b32_e32 v91, v192, v91
	v_cndmask_b32_e64 v192, 0, v91, s[16:17]
	s_movk_i32 s18, 5952
	v_ashrrev_i32_e32 v91, 31, v191
	v_cmp_le_i32_e64 s[16:17], s18, v90
	v_or_b32_e32 v91, 0x80000000, v91
	v_xor_b32_e32 v91, v191, v91
	v_cndmask_b32_e64 v191, 0, v91, s[16:17]
	s_movk_i32 s18, 6016
	v_ashrrev_i32_e32 v91, 31, v194
	v_cmp_le_i32_e64 s[16:17], s18, v90
	v_or_b32_e32 v91, 0x80000000, v91
	v_xor_b32_e32 v91, v194, v91
	v_cndmask_b32_e64 v194, 0, v91, s[16:17]
	s_movk_i32 s18, 6080
	v_ashrrev_i32_e32 v91, 31, v193
	v_cmp_le_i32_e64 s[16:17], s18, v90
	v_or_b32_e32 v91, 0x80000000, v91
	v_xor_b32_e32 v91, v193, v91
	v_cndmask_b32_e64 v193, 0, v91, s[16:17]
	s_waitcnt vmcnt(24)
	s_movk_i32 s18, 6144
	v_ashrrev_i32_e32 v91, 31, v196
	v_cmp_le_i32_e64 s[16:17], s18, v90
	v_or_b32_e32 v91, 0x80000000, v91
	v_xor_b32_e32 v91, v196, v91
	v_cndmask_b32_e64 v196, 0, v91, s[16:17]
	s_movk_i32 s18, 6208
	v_ashrrev_i32_e32 v91, 31, v195
	v_cmp_le_i32_e64 s[16:17], s18, v90
	v_or_b32_e32 v91, 0x80000000, v91
	v_xor_b32_e32 v91, v195, v91
	v_cndmask_b32_e64 v195, 0, v91, s[16:17]
	s_movk_i32 s18, 6272
	v_ashrrev_i32_e32 v91, 31, v198
	v_cmp_le_i32_e64 s[16:17], s18, v90
	v_or_b32_e32 v91, 0x80000000, v91
	v_xor_b32_e32 v91, v198, v91
	v_cndmask_b32_e64 v198, 0, v91, s[16:17]
	s_movk_i32 s18, 6336
	v_ashrrev_i32_e32 v91, 31, v197
	v_cmp_le_i32_e64 s[16:17], s18, v90
	v_or_b32_e32 v91, 0x80000000, v91
	v_xor_b32_e32 v91, v197, v91
	v_cndmask_b32_e64 v197, 0, v91, s[16:17]
	s_movk_i32 s18, 6400
	v_ashrrev_i32_e32 v91, 31, v200
	v_cmp_le_i32_e64 s[16:17], s18, v90
	v_or_b32_e32 v91, 0x80000000, v91
	v_xor_b32_e32 v91, v200, v91
	v_cndmask_b32_e64 v200, 0, v91, s[16:17]
	s_movk_i32 s18, 6464
	v_ashrrev_i32_e32 v91, 31, v199
	v_cmp_le_i32_e64 s[16:17], s18, v90
	v_or_b32_e32 v91, 0x80000000, v91
	v_xor_b32_e32 v91, v199, v91
	v_cndmask_b32_e64 v199, 0, v91, s[16:17]
	s_movk_i32 s18, 6528
	v_ashrrev_i32_e32 v91, 31, v202
	v_cmp_le_i32_e64 s[16:17], s18, v90
	v_or_b32_e32 v91, 0x80000000, v91
	v_xor_b32_e32 v91, v202, v91
	v_cndmask_b32_e64 v202, 0, v91, s[16:17]
	s_movk_i32 s18, 6592
	v_ashrrev_i32_e32 v91, 31, v201
	v_cmp_le_i32_e64 s[16:17], s18, v90
	v_or_b32_e32 v91, 0x80000000, v91
	v_xor_b32_e32 v91, v201, v91
	v_cndmask_b32_e64 v201, 0, v91, s[16:17]
	s_waitcnt vmcnt(16)
	s_movk_i32 s18, 6656
	v_ashrrev_i32_e32 v91, 31, v204
	v_cmp_le_i32_e64 s[16:17], s18, v90
	v_or_b32_e32 v91, 0x80000000, v91
	v_xor_b32_e32 v91, v204, v91
	v_cndmask_b32_e64 v204, 0, v91, s[16:17]
	s_movk_i32 s18, 6720
	v_ashrrev_i32_e32 v91, 31, v203
	v_cmp_le_i32_e64 s[16:17], s18, v90
	v_or_b32_e32 v91, 0x80000000, v91
	v_xor_b32_e32 v91, v203, v91
	v_cndmask_b32_e64 v203, 0, v91, s[16:17]
	s_movk_i32 s18, 6784
	v_ashrrev_i32_e32 v91, 31, v206
	v_cmp_le_i32_e64 s[16:17], s18, v90
	v_or_b32_e32 v91, 0x80000000, v91
	v_xor_b32_e32 v91, v206, v91
	v_cndmask_b32_e64 v206, 0, v91, s[16:17]
	s_movk_i32 s18, 6848
	v_ashrrev_i32_e32 v91, 31, v205
	v_cmp_le_i32_e64 s[16:17], s18, v90
	v_or_b32_e32 v91, 0x80000000, v91
	v_xor_b32_e32 v91, v205, v91
	v_cndmask_b32_e64 v205, 0, v91, s[16:17]
	s_movk_i32 s18, 6912
	v_ashrrev_i32_e32 v91, 31, v222
	v_cmp_le_i32_e64 s[16:17], s18, v90
	v_or_b32_e32 v91, 0x80000000, v91
	v_xor_b32_e32 v91, v222, v91
	v_cndmask_b32_e64 v222, 0, v91, s[16:17]
	s_movk_i32 s18, 6976
	v_ashrrev_i32_e32 v91, 31, v207
	v_cmp_le_i32_e64 s[16:17], s18, v90
	v_or_b32_e32 v91, 0x80000000, v91
	v_xor_b32_e32 v91, v207, v91
	v_cndmask_b32_e64 v207, 0, v91, s[16:17]
	s_movk_i32 s18, 7040
	v_ashrrev_i32_e32 v91, 31, v224
	v_cmp_le_i32_e64 s[16:17], s18, v90
	v_or_b32_e32 v91, 0x80000000, v91
	v_xor_b32_e32 v91, v224, v91
	v_cndmask_b32_e64 v224, 0, v91, s[16:17]
	s_movk_i32 s18, 7104
	v_ashrrev_i32_e32 v91, 31, v223
	v_cmp_le_i32_e64 s[16:17], s18, v90
	v_or_b32_e32 v91, 0x80000000, v91
	v_xor_b32_e32 v91, v223, v91
	v_cndmask_b32_e64 v223, 0, v91, s[16:17]
	s_waitcnt vmcnt(8)
	s_movk_i32 s18, 7168
	v_ashrrev_i32_e32 v91, 31, v226
	v_cmp_le_i32_e64 s[16:17], s18, v90
	v_or_b32_e32 v91, 0x80000000, v91
	v_xor_b32_e32 v91, v226, v91
	v_cndmask_b32_e64 v226, 0, v91, s[16:17]
	s_movk_i32 s18, 7232
	v_ashrrev_i32_e32 v91, 31, v225
	v_cmp_le_i32_e64 s[16:17], s18, v90
	v_or_b32_e32 v91, 0x80000000, v91
	v_xor_b32_e32 v91, v225, v91
	v_cndmask_b32_e64 v225, 0, v91, s[16:17]
	s_movk_i32 s18, 7296
	v_ashrrev_i32_e32 v91, 31, v228
	v_cmp_le_i32_e64 s[16:17], s18, v90
	v_or_b32_e32 v91, 0x80000000, v91
	v_xor_b32_e32 v91, v228, v91
	v_cndmask_b32_e64 v228, 0, v91, s[16:17]
	s_movk_i32 s18, 7360
	v_ashrrev_i32_e32 v91, 31, v227
	v_cmp_le_i32_e64 s[16:17], s18, v90
	v_or_b32_e32 v91, 0x80000000, v91
	v_xor_b32_e32 v91, v227, v91
	v_cndmask_b32_e64 v227, 0, v91, s[16:17]
	s_movk_i32 s18, 7424
	v_ashrrev_i32_e32 v91, 31, v230
	v_cmp_le_i32_e64 s[16:17], s18, v90
	v_or_b32_e32 v91, 0x80000000, v91
	v_xor_b32_e32 v91, v230, v91
	v_cndmask_b32_e64 v230, 0, v91, s[16:17]
	s_movk_i32 s18, 7488
	v_ashrrev_i32_e32 v91, 31, v229
	v_cmp_le_i32_e64 s[16:17], s18, v90
	v_or_b32_e32 v91, 0x80000000, v91
	v_xor_b32_e32 v91, v229, v91
	v_cndmask_b32_e64 v229, 0, v91, s[16:17]
	s_movk_i32 s18, 7552
	v_ashrrev_i32_e32 v91, 31, v232
	v_cmp_le_i32_e64 s[16:17], s18, v90
	v_or_b32_e32 v91, 0x80000000, v91
	v_xor_b32_e32 v91, v232, v91
	v_cndmask_b32_e64 v232, 0, v91, s[16:17]
	s_movk_i32 s18, 7616
	v_ashrrev_i32_e32 v91, 31, v231
	v_cmp_le_i32_e64 s[16:17], s18, v90
	v_or_b32_e32 v91, 0x80000000, v91
	v_xor_b32_e32 v91, v231, v91
	v_cndmask_b32_e64 v231, 0, v91, s[16:17]
	s_waitcnt vmcnt(0)
	s_movk_i32 s18, 7680
	v_ashrrev_i32_e32 v91, 31, v234
	v_cmp_le_i32_e64 s[16:17], s18, v90
	v_or_b32_e32 v91, 0x80000000, v91
	v_xor_b32_e32 v91, v234, v91
	v_cndmask_b32_e64 v234, 0, v91, s[16:17]
	s_movk_i32 s18, 7744
	v_ashrrev_i32_e32 v91, 31, v233
	v_cmp_le_i32_e64 s[16:17], s18, v90
	v_or_b32_e32 v91, 0x80000000, v91
	v_xor_b32_e32 v91, v233, v91
	v_cndmask_b32_e64 v233, 0, v91, s[16:17]
	s_movk_i32 s18, 7808
	v_ashrrev_i32_e32 v91, 31, v236
	v_cmp_le_i32_e64 s[16:17], s18, v90
	v_or_b32_e32 v91, 0x80000000, v91
	v_xor_b32_e32 v91, v236, v91
	v_cndmask_b32_e64 v236, 0, v91, s[16:17]
	s_movk_i32 s18, 7872
	v_ashrrev_i32_e32 v91, 31, v235
	v_cmp_le_i32_e64 s[16:17], s18, v90
	v_or_b32_e32 v91, 0x80000000, v91
	v_xor_b32_e32 v91, v235, v91
	v_cndmask_b32_e64 v235, 0, v91, s[16:17]
	s_movk_i32 s18, 7936
	v_ashrrev_i32_e32 v91, 31, v238
	v_cmp_le_i32_e64 s[16:17], s18, v90
	v_or_b32_e32 v91, 0x80000000, v91
	v_xor_b32_e32 v91, v238, v91
	v_cndmask_b32_e64 v238, 0, v91, s[16:17]
	s_movk_i32 s18, 8000
	v_ashrrev_i32_e32 v91, 31, v237
	v_cmp_le_i32_e64 s[16:17], s18, v90
	v_or_b32_e32 v91, 0x80000000, v91
	v_xor_b32_e32 v91, v237, v91
	v_cndmask_b32_e64 v237, 0, v91, s[16:17]
	s_movk_i32 s18, 8064
	v_ashrrev_i32_e32 v91, 31, v239
	v_cmp_le_i32_e64 s[16:17], s18, v90
	v_or_b32_e32 v91, 0x80000000, v91
	v_xor_b32_e32 v91, v239, v91
	v_cndmask_b32_e64 v239, 0, v91, s[16:17]
	s_movk_i32 s18, 8128
	v_ashrrev_i32_e32 v91, 31, v168
	v_cmp_le_i32_e64 s[16:17], s18, v90
	v_or_b32_e32 v91, 0x80000000, v91
	v_xor_b32_e32 v91, v168, v91
	v_cndmask_b32_e64 v168, 0, v91, s[16:17]
	s_waitcnt lgkmcnt(0)
	v_cmp_gt_i32_e64 s[16:17], s2, v153
	s_mov_b64 s[2:3], -1
	v_mov_b32_e32 v153, 0
	s_and_saveexec_b64 s[20:21], s[16:17]
	s_cbranch_execz .LBB0_686
	v_mov_b32_e32 v240, 0x100
	v_mov_b32_e32 v153, 0
	s_branch .LBB0_677

.LBB0_677:
	s_cmp_eq_u32 s39, 1
	s_cselect_b32 s18, 10, 0
	s_cmp_eq_u32 s39, 0
	s_cselect_b64 s[16:17], -1, 0
	s_and_b64 s[2:3], s[16:17], exec
	ds_write2st64_b32 v4, v0, v0 offset1:1
	ds_write2st64_b32 v4, v0, v0 offset0:2 offset1:3
	ds_write2st64_b32 v4, v0, v0 offset0:4 offset1:5
	ds_write2st64_b32 v4, v0, v0 offset0:6 offset1:7
	ds_write2st64_b32 v4, v0, v0 offset0:8 offset1:9
	ds_write2st64_b32 v4, v0, v0 offset0:10 offset1:11
	ds_write2st64_b32 v4, v0, v0 offset0:12 offset1:13
	ds_write2st64_b32 v4, v0, v0 offset0:14 offset1:15
	ds_write2st64_b32 v4, v0, v0 offset0:16 offset1:17
	ds_write2st64_b32 v4, v0, v0 offset0:18 offset1:19
	ds_write2st64_b32 v4, v0, v0 offset0:20 offset1:21
	ds_write2st64_b32 v4, v0, v0 offset0:22 offset1:23
	ds_write2st64_b32 v4, v0, v0 offset0:24 offset1:25
	ds_write2st64_b32 v4, v0, v0 offset0:26 offset1:27
	ds_write2st64_b32 v4, v0, v0 offset0:28 offset1:29
	ds_write2st64_b32 v4, v0, v0 offset0:30 offset1:31
	s_cselect_b32 s2, 21, s18
	s_cmp_eq_u32 s39, 2
	s_waitcnt lgkmcnt(0)
	s_cselect_b32 s24, 10, 11
	ds_read_b32 v210, v6 offset:36864
	s_add_i32 s18, s2, s24
	s_waitcnt lgkmcnt(14)
	v_lshlrev_b32_e32 v90, s18, v153
	s_lshl_b32 s18, -1, s18
	v_max_u32_e32 v91, 1, v90
	v_bitop3_b32 v90, v90, s18, v90 bitop3:0xf3
	v_cndmask_b32_e64 v91, v91, 1, s[16:17]
	v_cndmask_b32_e64 v90, v90, -1, s[16:17]
	s_lshl_b32 s3, -1, s24
	v_sub_u32_e32 v90, v90, v91
	s_waitcnt lgkmcnt(0)
	v_sub_u32_e32 v211, v210, v91
	v_lshrrev_b32_e32 v210, s2, v210
	v_bitop3_b32 v210, v210, s3, v210 bitop3:0x30
	v_cmp_gt_u32_e64 s[16:17], v211, v90
	v_sub_u32_e32 v212, v114, v91
	v_mov_b32_e32 v241, 0
	v_cndmask_b32_e64 v210, v210, v81, s[16:17]
	v_lshl_add_u32 v210, v210, 2, v79
	ds_add_u32 v210, v214
	ds_read_b32 v210, v6 offset:37120
	s_waitcnt lgkmcnt(0)
	v_sub_u32_e32 v211, v210, v91
	v_lshrrev_b32_e32 v210, s2, v210
	v_bitop3_b32 v210, v210, s3, v210 bitop3:0x30
	v_cmp_gt_u32_e64 s[16:17], v211, v90
	s_nop 1
	v_cndmask_b32_e64 v210, v210, v81, s[16:17]
	v_lshl_add_u32 v210, v210, 2, v79
	ds_add_u32 v210, v214
	ds_read_b32 v210, v6 offset:37376
	s_waitcnt lgkmcnt(0)
	v_sub_u32_e32 v211, v210, v91
	v_lshrrev_b32_e32 v210, s2, v210
	v_bitop3_b32 v210, v210, s3, v210 bitop3:0x30
	v_cmp_gt_u32_e64 s[16:17], v211, v90
	s_nop 1
	v_cndmask_b32_e64 v210, v210, v81, s[16:17]
	v_lshl_add_u32 v210, v210, 2, v79
	ds_add_u32 v210, v214
	ds_read_b32 v210, v6 offset:37632
	s_waitcnt lgkmcnt(0)
	v_sub_u32_e32 v211, v210, v91
	v_lshrrev_b32_e32 v210, s2, v210
	v_bitop3_b32 v210, v210, s3, v210 bitop3:0x30
	v_cmp_gt_u32_e64 s[16:17], v211, v90
	s_nop 1
	v_cndmask_b32_e64 v210, v210, v81, s[16:17]
	v_lshl_add_u32 v210, v210, 2, v79
	ds_add_u32 v210, v214
	ds_read_b32 v210, v6 offset:37888
	s_waitcnt lgkmcnt(0)
	v_sub_u32_e32 v211, v210, v91
	v_lshrrev_b32_e32 v210, s2, v210
	v_bitop3_b32 v210, v210, s3, v210 bitop3:0x30
	v_cmp_gt_u32_e64 s[16:17], v211, v90
	s_nop 1
	v_cndmask_b32_e64 v210, v210, v81, s[16:17]
	v_lshl_add_u32 v210, v210, 2, v79
	ds_add_u32 v210, v214
	ds_read_b32 v210, v6 offset:38144
	s_waitcnt lgkmcnt(0)
	v_sub_u32_e32 v211, v210, v91
	v_lshrrev_b32_e32 v210, s2, v210
	v_bitop3_b32 v210, v210, s3, v210 bitop3:0x30
	v_cmp_gt_u32_e64 s[16:17], v211, v90
	s_nop 1
	v_cndmask_b32_e64 v210, v210, v81, s[16:17]
	v_lshl_add_u32 v210, v210, 2, v79
	ds_add_u32 v210, v214
	ds_read_b32 v210, v6 offset:38400
	s_waitcnt lgkmcnt(0)
	v_sub_u32_e32 v211, v210, v91
	v_lshrrev_b32_e32 v210, s2, v210
	v_bitop3_b32 v210, v210, s3, v210 bitop3:0x30
	v_cmp_gt_u32_e64 s[16:17], v211, v90
	s_nop 1
	v_cndmask_b32_e64 v210, v210, v81, s[16:17]
	v_lshl_add_u32 v210, v210, 2, v79
	ds_add_u32 v210, v214
	ds_read_b32 v210, v6 offset:38656
	s_waitcnt lgkmcnt(0)
	v_sub_u32_e32 v211, v210, v91
	v_lshrrev_b32_e32 v210, s2, v210
	v_bitop3_b32 v210, v210, s3, v210 bitop3:0x30
	v_cmp_gt_u32_e64 s[16:17], v211, v90
	s_nop 1
	v_cndmask_b32_e64 v210, v210, v81, s[16:17]
	v_lshl_add_u32 v210, v210, 2, v79
	ds_add_u32 v210, v214
	ds_read_b32 v210, v6 offset:38912
	s_waitcnt lgkmcnt(0)
	v_sub_u32_e32 v211, v210, v91
	v_lshrrev_b32_e32 v210, s2, v210
	v_bitop3_b32 v210, v210, s3, v210 bitop3:0x30
	v_cmp_gt_u32_e64 s[16:17], v211, v90
	s_nop 1
	v_cndmask_b32_e64 v210, v210, v81, s[16:17]
	v_lshl_add_u32 v210, v210, 2, v79
	ds_add_u32 v210, v214
	ds_read_b32 v210, v6 offset:39168
	s_waitcnt lgkmcnt(0)
	v_sub_u32_e32 v211, v210, v91
	v_lshrrev_b32_e32 v210, s2, v210
	v_bitop3_b32 v210, v210, s3, v210 bitop3:0x30
	v_cmp_gt_u32_e64 s[16:17], v211, v90
	s_nop 1
	v_cndmask_b32_e64 v210, v210, v81, s[16:17]
	v_lshl_add_u32 v210, v210, 2, v79
	ds_add_u32 v210, v214
	ds_read_b32 v210, v6 offset:39424
	s_waitcnt lgkmcnt(0)
	v_sub_u32_e32 v211, v210, v91
	v_lshrrev_b32_e32 v210, s2, v210
	v_bitop3_b32 v210, v210, s3, v210 bitop3:0x30
	v_cmp_gt_u32_e64 s[16:17], v211, v90
	s_nop 1
	v_cndmask_b32_e64 v210, v210, v81, s[16:17]
	v_lshl_add_u32 v210, v210, 2, v79
	ds_add_u32 v210, v214
	ds_read_b32 v210, v6 offset:39680
	s_waitcnt lgkmcnt(0)
	v_sub_u32_e32 v211, v210, v91
	v_lshrrev_b32_e32 v210, s2, v210
	v_bitop3_b32 v210, v210, s3, v210 bitop3:0x30
	v_cmp_gt_u32_e64 s[16:17], v211, v90
	s_nop 1
	v_cndmask_b32_e64 v210, v210, v81, s[16:17]
	v_lshl_add_u32 v210, v210, 2, v79
	ds_add_u32 v210, v214
	ds_read_b32 v210, v6 offset:39936
	s_waitcnt lgkmcnt(0)
	v_sub_u32_e32 v211, v210, v91
	v_lshrrev_b32_e32 v210, s2, v210
	v_bitop3_b32 v210, v210, s3, v210 bitop3:0x30
	v_cmp_gt_u32_e64 s[16:17], v211, v90
	s_nop 1
	v_cndmask_b32_e64 v210, v210, v81, s[16:17]
	v_lshl_add_u32 v210, v210, 2, v79
	ds_add_u32 v210, v214
	ds_read_b32 v210, v6 offset:40192
	s_waitcnt lgkmcnt(0)
	v_sub_u32_e32 v211, v210, v91
	v_lshrrev_b32_e32 v210, s2, v210
	v_bitop3_b32 v210, v210, s3, v210 bitop3:0x30
	v_cmp_gt_u32_e64 s[16:17], v211, v90
	s_nop 1
	v_cndmask_b32_e64 v210, v210, v81, s[16:17]
	v_lshl_add_u32 v210, v210, 2, v79
	ds_add_u32 v210, v214
	ds_read_b32 v210, v6 offset:40448
	s_waitcnt lgkmcnt(0)
	v_sub_u32_e32 v211, v210, v91
	v_lshrrev_b32_e32 v210, s2, v210
	v_bitop3_b32 v210, v210, s3, v210 bitop3:0x30
	v_cmp_gt_u32_e64 s[16:17], v211, v90
	v_lshrrev_b32_e32 v211, s2, v114
	s_nop 0
	v_cndmask_b32_e64 v210, v210, v81, s[16:17]
	v_lshl_add_u32 v210, v210, 2, v79
	ds_add_u32 v210, v214
	ds_read_b32 v210, v6 offset:40704
	s_waitcnt lgkmcnt(0)
	v_sub_u32_e32 v213, v210, v91
	v_lshrrev_b32_e32 v210, s2, v210
	v_bitop3_b32 v210, v210, s3, v210 bitop3:0x30
	v_cmp_gt_u32_e64 s[16:17], v213, v90
	s_nop 1
	v_cndmask_b32_e64 v210, v210, v81, s[16:17]
	v_lshl_add_u32 v210, v210, 2, v79
	ds_add_u32 v210, v214
	v_bitop3_b32 v210, v211, s3, v211 bitop3:0x30
	v_cmp_gt_u32_e64 s[16:17], v212, v90
	v_lshrrev_b32_e32 v211, s2, v113
	v_bitop3_b32 v211, v211, s3, v211 bitop3:0x30
	v_cndmask_b32_e64 v210, v210, v81, s[16:17]
	v_lshl_add_u32 v210, v210, 2, v79
	ds_add_u32 v210, v214
	v_sub_u32_e32 v210, v113, v91
	v_cmp_gt_u32_e64 s[16:17], v210, v90
	s_nop 1
	v_cndmask_b32_e64 v210, v211, v81, s[16:17]
	v_lshl_add_u32 v210, v210, 2, v79
	ds_add_u32 v210, v214
	s_cmp_le_u32 m0, 1
	s_cbranch_scc1 .Lsel_pass_skip
	v_sub_u32_e32 v210, v116, v91
	v_lshrrev_b32_e32 v211, s2, v116
	v_bitop3_b32 v211, v211, s3, v211 bitop3:0x30
	v_cmp_gt_u32_e64 s[16:17], v210, v90
	s_nop 1
	v_cndmask_b32_e64 v210, v211, v81, s[16:17]
	v_lshl_add_u32 v210, v210, 2, v79
	ds_add_u32 v210, v214
	v_sub_u32_e32 v210, v115, v91
	v_lshrrev_b32_e32 v211, s2, v115
	v_bitop3_b32 v211, v211, s3, v211 bitop3:0x30
	v_cmp_gt_u32_e64 s[16:17], v210, v90
	s_nop 1
	v_cndmask_b32_e64 v210, v211, v81, s[16:17]
	v_lshl_add_u32 v210, v210, 2, v79
	ds_add_u32 v210, v214
	v_sub_u32_e32 v210, v118, v91
	v_lshrrev_b32_e32 v211, s2, v118
	v_bitop3_b32 v211, v211, s3, v211 bitop3:0x30
	v_cmp_gt_u32_e64 s[16:17], v210, v90
	s_nop 1
	v_cndmask_b32_e64 v210, v211, v81, s[16:17]
	v_lshl_add_u32 v210, v210, 2, v79
	ds_add_u32 v210, v214
	v_sub_u32_e32 v210, v117, v91
	v_lshrrev_b32_e32 v211, s2, v117
	v_bitop3_b32 v211, v211, s3, v211 bitop3:0x30
	v_cmp_gt_u32_e64 s[16:17], v210, v90
	s_nop 1
	v_cndmask_b32_e64 v210, v211, v81, s[16:17]
	v_lshl_add_u32 v210, v210, 2, v79
	ds_add_u32 v210, v214
	v_sub_u32_e32 v210, v120, v91
	v_lshrrev_b32_e32 v211, s2, v120
	v_bitop3_b32 v211, v211, s3, v211 bitop3:0x30
	v_cmp_gt_u32_e64 s[16:17], v210, v90
	s_nop 1
	v_cndmask_b32_e64 v210, v211, v81, s[16:17]
	v_lshl_add_u32 v210, v210, 2, v79
	ds_add_u32 v210, v214
	v_sub_u32_e32 v210, v119, v91
	v_lshrrev_b32_e32 v211, s2, v119
	v_bitop3_b32 v211, v211, s3, v211 bitop3:0x30
	v_cmp_gt_u32_e64 s[16:17], v210, v90
	s_nop 1
	v_cndmask_b32_e64 v210, v211, v81, s[16:17]
	v_lshl_add_u32 v210, v210, 2, v79
	ds_add_u32 v210, v214
	v_sub_u32_e32 v210, v122, v91
	v_lshrrev_b32_e32 v211, s2, v122
	v_bitop3_b32 v211, v211, s3, v211 bitop3:0x30
	v_cmp_gt_u32_e64 s[16:17], v210, v90
	s_nop 1
	v_cndmask_b32_e64 v210, v211, v81, s[16:17]
	v_lshl_add_u32 v210, v210, 2, v79
	ds_add_u32 v210, v214
	v_sub_u32_e32 v210, v121, v91
	v_lshrrev_b32_e32 v211, s2, v121
	v_bitop3_b32 v211, v211, s3, v211 bitop3:0x30
	v_cmp_gt_u32_e64 s[16:17], v210, v90
	s_nop 1
	v_cndmask_b32_e64 v210, v211, v81, s[16:17]
	v_lshl_add_u32 v210, v210, 2, v79
	ds_add_u32 v210, v214
	v_sub_u32_e32 v210, v124, v91
	v_lshrrev_b32_e32 v211, s2, v124
	v_bitop3_b32 v211, v211, s3, v211 bitop3:0x30
	v_cmp_gt_u32_e64 s[16:17], v210, v90
	s_nop 1
	v_cndmask_b32_e64 v210, v211, v81, s[16:17]
	v_lshl_add_u32 v210, v210, 2, v79
	ds_add_u32 v210, v214
	v_sub_u32_e32 v210, v123, v91
	v_lshrrev_b32_e32 v211, s2, v123
	v_bitop3_b32 v211, v211, s3, v211 bitop3:0x30
	v_cmp_gt_u32_e64 s[16:17], v210, v90
	s_nop 1
	v_cndmask_b32_e64 v210, v211, v81, s[16:17]
	v_lshl_add_u32 v210, v210, 2, v79
	ds_add_u32 v210, v214
	v_sub_u32_e32 v210, v126, v91
	v_lshrrev_b32_e32 v211, s2, v126
	v_bitop3_b32 v211, v211, s3, v211 bitop3:0x30
	v_cmp_gt_u32_e64 s[16:17], v210, v90
	s_nop 1
	v_cndmask_b32_e64 v210, v211, v81, s[16:17]
	v_lshl_add_u32 v210, v210, 2, v79
	ds_add_u32 v210, v214
	v_sub_u32_e32 v210, v125, v91
	v_lshrrev_b32_e32 v211, s2, v125
	v_bitop3_b32 v211, v211, s3, v211 bitop3:0x30
	v_cmp_gt_u32_e64 s[16:17], v210, v90
	s_nop 1
	v_cndmask_b32_e64 v210, v211, v81, s[16:17]
	v_lshl_add_u32 v210, v210, 2, v79
	ds_add_u32 v210, v214
	v_sub_u32_e32 v210, v128, v91
	v_lshrrev_b32_e32 v211, s2, v128
	v_bitop3_b32 v211, v211, s3, v211 bitop3:0x30
	v_cmp_gt_u32_e64 s[16:17], v210, v90
	s_nop 1
	v_cndmask_b32_e64 v210, v211, v81, s[16:17]
	v_lshl_add_u32 v210, v210, 2, v79
	ds_add_u32 v210, v214
	v_sub_u32_e32 v210, v127, v91
	v_lshrrev_b32_e32 v211, s2, v127
	v_bitop3_b32 v211, v211, s3, v211 bitop3:0x30
	v_cmp_gt_u32_e64 s[16:17], v210, v90
	s_nop 1
	v_cndmask_b32_e64 v210, v211, v81, s[16:17]
	v_lshl_add_u32 v210, v210, 2, v79
	ds_add_u32 v210, v214
	s_cmp_le_u32 m0, 2
	s_cbranch_scc1 .Lsel_pass_skip
	v_sub_u32_e32 v210, v130, v91
	v_lshrrev_b32_e32 v211, s2, v130
	v_bitop3_b32 v211, v211, s3, v211 bitop3:0x30
	v_cmp_gt_u32_e64 s[16:17], v210, v90
	s_nop 1
	v_cndmask_b32_e64 v210, v211, v81, s[16:17]
	v_lshl_add_u32 v210, v210, 2, v79
	ds_add_u32 v210, v214
	v_sub_u32_e32 v210, v129, v91
	v_lshrrev_b32_e32 v211, s2, v129
	v_bitop3_b32 v211, v211, s3, v211 bitop3:0x30
	v_cmp_gt_u32_e64 s[16:17], v210, v90
	s_nop 1
	v_cndmask_b32_e64 v210, v211, v81, s[16:17]
	v_lshl_add_u32 v210, v210, 2, v79
	ds_add_u32 v210, v214
	v_sub_u32_e32 v210, v132, v91
	v_lshrrev_b32_e32 v211, s2, v132
	v_bitop3_b32 v211, v211, s3, v211 bitop3:0x30
	v_cmp_gt_u32_e64 s[16:17], v210, v90
	s_nop 1
	v_cndmask_b32_e64 v210, v211, v81, s[16:17]
	v_lshl_add_u32 v210, v210, 2, v79
	ds_add_u32 v210, v214
	v_sub_u32_e32 v210, v131, v91
	v_lshrrev_b32_e32 v211, s2, v131
	v_bitop3_b32 v211, v211, s3, v211 bitop3:0x30
	v_cmp_gt_u32_e64 s[16:17], v210, v90
	s_nop 1
	v_cndmask_b32_e64 v210, v211, v81, s[16:17]
	v_lshl_add_u32 v210, v210, 2, v79
	ds_add_u32 v210, v214
	v_sub_u32_e32 v210, v134, v91
	v_lshrrev_b32_e32 v211, s2, v134
	v_bitop3_b32 v211, v211, s3, v211 bitop3:0x30
	v_cmp_gt_u32_e64 s[16:17], v210, v90
	s_nop 1
	v_cndmask_b32_e64 v210, v211, v81, s[16:17]
	v_lshl_add_u32 v210, v210, 2, v79
	ds_add_u32 v210, v214
	v_sub_u32_e32 v210, v133, v91
	v_lshrrev_b32_e32 v211, s2, v133
	v_bitop3_b32 v211, v211, s3, v211 bitop3:0x30
	v_cmp_gt_u32_e64 s[16:17], v210, v90
	s_nop 1
	v_cndmask_b32_e64 v210, v211, v81, s[16:17]
	v_lshl_add_u32 v210, v210, 2, v79
	ds_add_u32 v210, v214
	v_sub_u32_e32 v210, v136, v91
	v_lshrrev_b32_e32 v211, s2, v136
	v_bitop3_b32 v211, v211, s3, v211 bitop3:0x30
	v_cmp_gt_u32_e64 s[16:17], v210, v90
	s_nop 1
	v_cndmask_b32_e64 v210, v211, v81, s[16:17]
	v_lshl_add_u32 v210, v210, 2, v79
	ds_add_u32 v210, v214
	v_sub_u32_e32 v210, v135, v91
	v_lshrrev_b32_e32 v211, s2, v135
	v_bitop3_b32 v211, v211, s3, v211 bitop3:0x30
	v_cmp_gt_u32_e64 s[16:17], v210, v90
	s_nop 1
	v_cndmask_b32_e64 v210, v211, v81, s[16:17]
	v_lshl_add_u32 v210, v210, 2, v79
	ds_add_u32 v210, v214
	v_sub_u32_e32 v210, v138, v91
	v_lshrrev_b32_e32 v211, s2, v138
	v_bitop3_b32 v211, v211, s3, v211 bitop3:0x30
	v_cmp_gt_u32_e64 s[16:17], v210, v90
	s_nop 1
	v_cndmask_b32_e64 v210, v211, v81, s[16:17]
	v_lshl_add_u32 v210, v210, 2, v79
	ds_add_u32 v210, v214
	v_sub_u32_e32 v210, v137, v91
	v_lshrrev_b32_e32 v211, s2, v137
	v_bitop3_b32 v211, v211, s3, v211 bitop3:0x30
	v_cmp_gt_u32_e64 s[16:17], v210, v90
	s_nop 1
	v_cndmask_b32_e64 v210, v211, v81, s[16:17]
	v_lshl_add_u32 v210, v210, 2, v79
	ds_add_u32 v210, v214
	v_sub_u32_e32 v210, v140, v91
	v_lshrrev_b32_e32 v211, s2, v140
	v_bitop3_b32 v211, v211, s3, v211 bitop3:0x30
	v_cmp_gt_u32_e64 s[16:17], v210, v90
	s_nop 1
	v_cndmask_b32_e64 v210, v211, v81, s[16:17]
	v_lshl_add_u32 v210, v210, 2, v79
	ds_add_u32 v210, v214
	v_sub_u32_e32 v210, v139, v91
	v_lshrrev_b32_e32 v211, s2, v139
	v_bitop3_b32 v211, v211, s3, v211 bitop3:0x30
	v_cmp_gt_u32_e64 s[16:17], v210, v90
	s_nop 1
	v_cndmask_b32_e64 v210, v211, v81, s[16:17]
	v_lshl_add_u32 v210, v210, 2, v79
	ds_add_u32 v210, v214
	v_sub_u32_e32 v210, v142, v91
	v_lshrrev_b32_e32 v211, s2, v142
	v_bitop3_b32 v211, v211, s3, v211 bitop3:0x30
	v_cmp_gt_u32_e64 s[16:17], v210, v90
	s_nop 1
	v_cndmask_b32_e64 v210, v211, v81, s[16:17]
	v_lshl_add_u32 v210, v210, 2, v79
	ds_add_u32 v210, v214
	v_sub_u32_e32 v210, v141, v91
	v_lshrrev_b32_e32 v211, s2, v141
	v_bitop3_b32 v211, v211, s3, v211 bitop3:0x30
	v_cmp_gt_u32_e64 s[16:17], v210, v90
	s_nop 1
	v_cndmask_b32_e64 v210, v211, v81, s[16:17]
	v_lshl_add_u32 v210, v210, 2, v79
	ds_add_u32 v210, v214
	v_sub_u32_e32 v210, v144, v91
	v_lshrrev_b32_e32 v211, s2, v144
	v_bitop3_b32 v211, v211, s3, v211 bitop3:0x30
	v_cmp_gt_u32_e64 s[16:17], v210, v90
	s_nop 1
	v_cndmask_b32_e64 v210, v211, v81, s[16:17]
	v_lshl_add_u32 v210, v210, 2, v79
	ds_add_u32 v210, v214
	v_sub_u32_e32 v210, v143, v91
	v_lshrrev_b32_e32 v211, s2, v143
	v_bitop3_b32 v211, v211, s3, v211 bitop3:0x30
	v_cmp_gt_u32_e64 s[16:17], v210, v90
	s_nop 1
	v_cndmask_b32_e64 v210, v211, v81, s[16:17]
	v_lshl_add_u32 v210, v210, 2, v79
	ds_add_u32 v210, v214
	s_cmp_le_u32 m0, 3
	s_cbranch_scc1 .Lsel_pass_skip
	v_sub_u32_e32 v210, v146, v91
	v_lshrrev_b32_e32 v211, s2, v146
	v_bitop3_b32 v211, v211, s3, v211 bitop3:0x30
	v_cmp_gt_u32_e64 s[16:17], v210, v90
	s_nop 1
	v_cndmask_b32_e64 v210, v211, v81, s[16:17]
	v_lshl_add_u32 v210, v210, 2, v79
	ds_add_u32 v210, v214
	v_sub_u32_e32 v210, v145, v91
	v_lshrrev_b32_e32 v211, s2, v145
	v_bitop3_b32 v211, v211, s3, v211 bitop3:0x30
	v_cmp_gt_u32_e64 s[16:17], v210, v90
	s_nop 1
	v_cndmask_b32_e64 v210, v211, v81, s[16:17]
	v_lshl_add_u32 v210, v210, 2, v79
	ds_add_u32 v210, v214
	v_sub_u32_e32 v210, v148, v91
	v_lshrrev_b32_e32 v211, s2, v148
	v_bitop3_b32 v211, v211, s3, v211 bitop3:0x30
	v_cmp_gt_u32_e64 s[16:17], v210, v90
	s_nop 1
	v_cndmask_b32_e64 v210, v211, v81, s[16:17]
	v_lshl_add_u32 v210, v210, 2, v79
	ds_add_u32 v210, v214
	v_sub_u32_e32 v210, v147, v91
	v_lshrrev_b32_e32 v211, s2, v147
	v_bitop3_b32 v211, v211, s3, v211 bitop3:0x30
	v_cmp_gt_u32_e64 s[16:17], v210, v90
	s_nop 1
	v_cndmask_b32_e64 v210, v211, v81, s[16:17]
	v_lshl_add_u32 v210, v210, 2, v79
	ds_add_u32 v210, v214
	v_sub_u32_e32 v210, v150, v91
	v_lshrrev_b32_e32 v211, s2, v150
	v_bitop3_b32 v211, v211, s3, v211 bitop3:0x30
	v_cmp_gt_u32_e64 s[16:17], v210, v90
	s_nop 1
	v_cndmask_b32_e64 v210, v211, v81, s[16:17]
	v_lshl_add_u32 v210, v210, 2, v79
	ds_add_u32 v210, v214
	v_sub_u32_e32 v210, v149, v91
	v_lshrrev_b32_e32 v211, s2, v149
	v_bitop3_b32 v211, v211, s3, v211 bitop3:0x30
	v_cmp_gt_u32_e64 s[16:17], v210, v90
	s_nop 1
	v_cndmask_b32_e64 v210, v211, v81, s[16:17]
	v_lshl_add_u32 v210, v210, 2, v79
	ds_add_u32 v210, v214
	v_sub_u32_e32 v210, v152, v91
	v_lshrrev_b32_e32 v211, s2, v152
	v_bitop3_b32 v211, v211, s3, v211 bitop3:0x30
	v_cmp_gt_u32_e64 s[16:17], v210, v90
	s_nop 1
	v_cndmask_b32_e64 v210, v211, v81, s[16:17]
	v_lshl_add_u32 v210, v210, 2, v79
	ds_add_u32 v210, v214
	v_sub_u32_e32 v210, v151, v91
	v_lshrrev_b32_e32 v211, s2, v151
	v_bitop3_b32 v211, v211, s3, v211 bitop3:0x30
	v_cmp_gt_u32_e64 s[16:17], v210, v90
	s_nop 1
	v_cndmask_b32_e64 v210, v211, v81, s[16:17]
	v_lshl_add_u32 v210, v210, 2, v79
	ds_add_u32 v210, v214
	v_sub_u32_e32 v210, v155, v91
	v_lshrrev_b32_e32 v211, s2, v155
	v_bitop3_b32 v211, v211, s3, v211 bitop3:0x30
	v_cmp_gt_u32_e64 s[16:17], v210, v90
	s_nop 1
	v_cndmask_b32_e64 v210, v211, v81, s[16:17]
	v_lshl_add_u32 v210, v210, 2, v79
	ds_add_u32 v210, v214
	v_sub_u32_e32 v210, v154, v91
	v_lshrrev_b32_e32 v211, s2, v154
	v_bitop3_b32 v211, v211, s3, v211 bitop3:0x30
	v_cmp_gt_u32_e64 s[16:17], v210, v90
	s_nop 1
	v_cndmask_b32_e64 v210, v211, v81, s[16:17]
	v_lshl_add_u32 v210, v210, 2, v79
	ds_add_u32 v210, v214
	v_sub_u32_e32 v210, v157, v91
	v_lshrrev_b32_e32 v211, s2, v157
	v_bitop3_b32 v211, v211, s3, v211 bitop3:0x30
	v_cmp_gt_u32_e64 s[16:17], v210, v90
	s_nop 1
	v_cndmask_b32_e64 v210, v211, v81, s[16:17]
	v_lshl_add_u32 v210, v210, 2, v79
	ds_add_u32 v210, v214
	v_sub_u32_e32 v210, v156, v91
	v_lshrrev_b32_e32 v211, s2, v156
	v_bitop3_b32 v211, v211, s3, v211 bitop3:0x30
	v_cmp_gt_u32_e64 s[16:17], v210, v90
	s_nop 1
	v_cndmask_b32_e64 v210, v211, v81, s[16:17]
	v_lshl_add_u32 v210, v210, 2, v79
	ds_add_u32 v210, v214
	v_sub_u32_e32 v210, v159, v91
	v_lshrrev_b32_e32 v211, s2, v159
	v_bitop3_b32 v211, v211, s3, v211 bitop3:0x30
	v_cmp_gt_u32_e64 s[16:17], v210, v90
	s_nop 1
	v_cndmask_b32_e64 v210, v211, v81, s[16:17]
	v_lshl_add_u32 v210, v210, 2, v79
	ds_add_u32 v210, v214
	v_sub_u32_e32 v210, v158, v91
	v_lshrrev_b32_e32 v211, s2, v158
	v_bitop3_b32 v211, v211, s3, v211 bitop3:0x30
	v_cmp_gt_u32_e64 s[16:17], v210, v90
	s_nop 1
	v_cndmask_b32_e64 v210, v211, v81, s[16:17]
	v_lshl_add_u32 v210, v210, 2, v79
	ds_add_u32 v210, v214
	v_sub_u32_e32 v210, v161, v91
	v_lshrrev_b32_e32 v211, s2, v161
	v_bitop3_b32 v211, v211, s3, v211 bitop3:0x30
	v_cmp_gt_u32_e64 s[16:17], v210, v90
	s_nop 1
	v_cndmask_b32_e64 v210, v211, v81, s[16:17]
	v_lshl_add_u32 v210, v210, 2, v79
	ds_add_u32 v210, v214
	v_sub_u32_e32 v210, v160, v91
	v_lshrrev_b32_e32 v211, s2, v160
	v_bitop3_b32 v211, v211, s3, v211 bitop3:0x30
	v_cmp_gt_u32_e64 s[16:17], v210, v90
	s_nop 1
	v_cndmask_b32_e64 v210, v211, v81, s[16:17]
	v_lshl_add_u32 v210, v210, 2, v79
	ds_add_u32 v210, v214
	s_cmp_le_u32 m0, 4
	s_cbranch_scc1 .Lsel_pass_skip
	v_sub_u32_e32 v210, v163, v91
	v_lshrrev_b32_e32 v211, s2, v163
	v_bitop3_b32 v211, v211, s3, v211 bitop3:0x30
	v_cmp_gt_u32_e64 s[16:17], v210, v90
	s_nop 1
	v_cndmask_b32_e64 v210, v211, v81, s[16:17]
	v_lshl_add_u32 v210, v210, 2, v79
	ds_add_u32 v210, v214
	v_sub_u32_e32 v210, v162, v91
	v_lshrrev_b32_e32 v211, s2, v162
	v_bitop3_b32 v211, v211, s3, v211 bitop3:0x30
	v_cmp_gt_u32_e64 s[16:17], v210, v90
	s_nop 1
	v_cndmask_b32_e64 v210, v211, v81, s[16:17]
	v_lshl_add_u32 v210, v210, 2, v79
	ds_add_u32 v210, v214
	v_sub_u32_e32 v210, v165, v91
	v_lshrrev_b32_e32 v211, s2, v165
	v_bitop3_b32 v211, v211, s3, v211 bitop3:0x30
	v_cmp_gt_u32_e64 s[16:17], v210, v90
	s_nop 1
	v_cndmask_b32_e64 v210, v211, v81, s[16:17]
	v_lshl_add_u32 v210, v210, 2, v79
	ds_add_u32 v210, v214
	v_sub_u32_e32 v210, v164, v91
	v_lshrrev_b32_e32 v211, s2, v164
	v_bitop3_b32 v211, v211, s3, v211 bitop3:0x30
	v_cmp_gt_u32_e64 s[16:17], v210, v90
	s_nop 1
	v_cndmask_b32_e64 v210, v211, v81, s[16:17]
	v_lshl_add_u32 v210, v210, 2, v79
	ds_add_u32 v210, v214
	v_sub_u32_e32 v210, v167, v91
	v_lshrrev_b32_e32 v211, s2, v167
	v_bitop3_b32 v211, v211, s3, v211 bitop3:0x30
	v_cmp_gt_u32_e64 s[16:17], v210, v90
	s_nop 1
	v_cndmask_b32_e64 v210, v211, v81, s[16:17]
	v_lshl_add_u32 v210, v210, 2, v79
	ds_add_u32 v210, v214
	v_sub_u32_e32 v210, v166, v91
	v_lshrrev_b32_e32 v211, s2, v166
	v_bitop3_b32 v211, v211, s3, v211 bitop3:0x30
	v_cmp_gt_u32_e64 s[16:17], v210, v90
	s_nop 1
	v_cndmask_b32_e64 v210, v211, v81, s[16:17]
	v_lshl_add_u32 v210, v210, 2, v79
	ds_add_u32 v210, v214
	v_sub_u32_e32 v210, v170, v91
	v_lshrrev_b32_e32 v211, s2, v170
	v_bitop3_b32 v211, v211, s3, v211 bitop3:0x30
	v_cmp_gt_u32_e64 s[16:17], v210, v90
	s_nop 1
	v_cndmask_b32_e64 v210, v211, v81, s[16:17]
	v_lshl_add_u32 v210, v210, 2, v79
	ds_add_u32 v210, v214
	v_sub_u32_e32 v210, v169, v91
	v_lshrrev_b32_e32 v211, s2, v169
	v_bitop3_b32 v211, v211, s3, v211 bitop3:0x30
	v_cmp_gt_u32_e64 s[16:17], v210, v90
	s_nop 1
	v_cndmask_b32_e64 v210, v211, v81, s[16:17]
	v_lshl_add_u32 v210, v210, 2, v79
	ds_add_u32 v210, v214
	v_sub_u32_e32 v210, v172, v91
	v_lshrrev_b32_e32 v211, s2, v172
	v_bitop3_b32 v211, v211, s3, v211 bitop3:0x30
	v_cmp_gt_u32_e64 s[16:17], v210, v90
	s_nop 1
	v_cndmask_b32_e64 v210, v211, v81, s[16:17]
	v_lshl_add_u32 v210, v210, 2, v79
	ds_add_u32 v210, v214
	v_sub_u32_e32 v210, v171, v91
	v_lshrrev_b32_e32 v211, s2, v171
	v_bitop3_b32 v211, v211, s3, v211 bitop3:0x30
	v_cmp_gt_u32_e64 s[16:17], v210, v90
	s_nop 1
	v_cndmask_b32_e64 v210, v211, v81, s[16:17]
	v_lshl_add_u32 v210, v210, 2, v79
	ds_add_u32 v210, v214
	v_sub_u32_e32 v210, v174, v91
	v_lshrrev_b32_e32 v211, s2, v174
	v_bitop3_b32 v211, v211, s3, v211 bitop3:0x30
	v_cmp_gt_u32_e64 s[16:17], v210, v90
	s_nop 1
	v_cndmask_b32_e64 v210, v211, v81, s[16:17]
	v_lshl_add_u32 v210, v210, 2, v79
	ds_add_u32 v210, v214
	v_sub_u32_e32 v210, v173, v91
	v_lshrrev_b32_e32 v211, s2, v173
	v_bitop3_b32 v211, v211, s3, v211 bitop3:0x30
	v_cmp_gt_u32_e64 s[16:17], v210, v90
	s_nop 1
	v_cndmask_b32_e64 v210, v211, v81, s[16:17]
	v_lshl_add_u32 v210, v210, 2, v79
	ds_add_u32 v210, v214
	v_sub_u32_e32 v210, v176, v91
	v_lshrrev_b32_e32 v211, s2, v176
	v_bitop3_b32 v211, v211, s3, v211 bitop3:0x30
	v_cmp_gt_u32_e64 s[16:17], v210, v90
	s_nop 1
	v_cndmask_b32_e64 v210, v211, v81, s[16:17]
	v_lshl_add_u32 v210, v210, 2, v79
	ds_add_u32 v210, v214
	v_sub_u32_e32 v210, v175, v91
	v_lshrrev_b32_e32 v211, s2, v175
	v_bitop3_b32 v211, v211, s3, v211 bitop3:0x30
	v_cmp_gt_u32_e64 s[16:17], v210, v90
	s_nop 1
	v_cndmask_b32_e64 v210, v211, v81, s[16:17]
	v_lshl_add_u32 v210, v210, 2, v79
	ds_add_u32 v210, v214
	v_sub_u32_e32 v210, v178, v91
	v_lshrrev_b32_e32 v211, s2, v178
	v_bitop3_b32 v211, v211, s3, v211 bitop3:0x30
	v_cmp_gt_u32_e64 s[16:17], v210, v90
	s_nop 1
	v_cndmask_b32_e64 v210, v211, v81, s[16:17]
	v_lshl_add_u32 v210, v210, 2, v79
	ds_add_u32 v210, v214
	v_sub_u32_e32 v210, v177, v91
	v_lshrrev_b32_e32 v211, s2, v177
	v_bitop3_b32 v211, v211, s3, v211 bitop3:0x30
	v_cmp_gt_u32_e64 s[16:17], v210, v90
	s_nop 1
	v_cndmask_b32_e64 v210, v211, v81, s[16:17]
	v_lshl_add_u32 v210, v210, 2, v79
	ds_add_u32 v210, v214
	s_cmp_le_u32 m0, 5
	s_cbranch_scc1 .Lsel_pass_skip
	v_sub_u32_e32 v210, v180, v91
	v_lshrrev_b32_e32 v211, s2, v180
	v_bitop3_b32 v211, v211, s3, v211 bitop3:0x30
	v_cmp_gt_u32_e64 s[16:17], v210, v90
	s_nop 1
	v_cndmask_b32_e64 v210, v211, v81, s[16:17]
	v_lshl_add_u32 v210, v210, 2, v79
	ds_add_u32 v210, v214
	v_sub_u32_e32 v210, v179, v91
	v_lshrrev_b32_e32 v211, s2, v179
	v_bitop3_b32 v211, v211, s3, v211 bitop3:0x30
	v_cmp_gt_u32_e64 s[16:17], v210, v90
	s_nop 1
	v_cndmask_b32_e64 v210, v211, v81, s[16:17]
	v_lshl_add_u32 v210, v210, 2, v79
	ds_add_u32 v210, v214
	v_sub_u32_e32 v210, v182, v91
	v_lshrrev_b32_e32 v211, s2, v182
	v_bitop3_b32 v211, v211, s3, v211 bitop3:0x30
	v_cmp_gt_u32_e64 s[16:17], v210, v90
	s_nop 1
	v_cndmask_b32_e64 v210, v211, v81, s[16:17]
	v_lshl_add_u32 v210, v210, 2, v79
	ds_add_u32 v210, v214
	v_sub_u32_e32 v210, v181, v91
	v_lshrrev_b32_e32 v211, s2, v181
	v_bitop3_b32 v211, v211, s3, v211 bitop3:0x30
	v_cmp_gt_u32_e64 s[16:17], v210, v90
	s_nop 1
	v_cndmask_b32_e64 v210, v211, v81, s[16:17]
	v_lshl_add_u32 v210, v210, 2, v79
	ds_add_u32 v210, v214
	v_sub_u32_e32 v210, v184, v91
	v_lshrrev_b32_e32 v211, s2, v184
	v_bitop3_b32 v211, v211, s3, v211 bitop3:0x30
	v_cmp_gt_u32_e64 s[16:17], v210, v90
	s_nop 1
	v_cndmask_b32_e64 v210, v211, v81, s[16:17]
	v_lshl_add_u32 v210, v210, 2, v79
	ds_add_u32 v210, v214
	v_sub_u32_e32 v210, v183, v91
	v_lshrrev_b32_e32 v211, s2, v183
	v_bitop3_b32 v211, v211, s3, v211 bitop3:0x30
	v_cmp_gt_u32_e64 s[16:17], v210, v90
	s_nop 1
	v_cndmask_b32_e64 v210, v211, v81, s[16:17]
	v_lshl_add_u32 v210, v210, 2, v79
	ds_add_u32 v210, v214
	v_sub_u32_e32 v210, v186, v91
	v_lshrrev_b32_e32 v211, s2, v186
	v_bitop3_b32 v211, v211, s3, v211 bitop3:0x30
	v_cmp_gt_u32_e64 s[16:17], v210, v90
	s_nop 1
	v_cndmask_b32_e64 v210, v211, v81, s[16:17]
	v_lshl_add_u32 v210, v210, 2, v79
	ds_add_u32 v210, v214
	v_sub_u32_e32 v210, v185, v91
	v_lshrrev_b32_e32 v211, s2, v185
	v_bitop3_b32 v211, v211, s3, v211 bitop3:0x30
	v_cmp_gt_u32_e64 s[16:17], v210, v90
	s_nop 1
	v_cndmask_b32_e64 v210, v211, v81, s[16:17]
	v_lshl_add_u32 v210, v210, 2, v79
	ds_add_u32 v210, v214
	v_sub_u32_e32 v210, v188, v91
	v_lshrrev_b32_e32 v211, s2, v188
	v_bitop3_b32 v211, v211, s3, v211 bitop3:0x30
	v_cmp_gt_u32_e64 s[16:17], v210, v90
	s_nop 1
	v_cndmask_b32_e64 v210, v211, v81, s[16:17]
	v_lshl_add_u32 v210, v210, 2, v79
	ds_add_u32 v210, v214
	v_sub_u32_e32 v210, v187, v91
	v_lshrrev_b32_e32 v211, s2, v187
	v_bitop3_b32 v211, v211, s3, v211 bitop3:0x30
	v_cmp_gt_u32_e64 s[16:17], v210, v90
	s_nop 1
	v_cndmask_b32_e64 v210, v211, v81, s[16:17]
	v_lshl_add_u32 v210, v210, 2, v79
	ds_add_u32 v210, v214
	v_sub_u32_e32 v210, v190, v91
	v_lshrrev_b32_e32 v211, s2, v190
	v_bitop3_b32 v211, v211, s3, v211 bitop3:0x30
	v_cmp_gt_u32_e64 s[16:17], v210, v90
	s_nop 1
	v_cndmask_b32_e64 v210, v211, v81, s[16:17]
	v_lshl_add_u32 v210, v210, 2, v79
	ds_add_u32 v210, v214
	v_sub_u32_e32 v210, v189, v91
	v_lshrrev_b32_e32 v211, s2, v189
	v_bitop3_b32 v211, v211, s3, v211 bitop3:0x30
	v_cmp_gt_u32_e64 s[16:17], v210, v90
	s_nop 1
	v_cndmask_b32_e64 v210, v211, v81, s[16:17]
	v_lshl_add_u32 v210, v210, 2, v79
	ds_add_u32 v210, v214
	v_sub_u32_e32 v210, v192, v91
	v_lshrrev_b32_e32 v211, s2, v192
	v_bitop3_b32 v211, v211, s3, v211 bitop3:0x30
	v_cmp_gt_u32_e64 s[16:17], v210, v90
	s_nop 1
	v_cndmask_b32_e64 v210, v211, v81, s[16:17]
	v_lshl_add_u32 v210, v210, 2, v79
	ds_add_u32 v210, v214
	v_sub_u32_e32 v210, v191, v91
	v_lshrrev_b32_e32 v211, s2, v191
	v_bitop3_b32 v211, v211, s3, v211 bitop3:0x30
	v_cmp_gt_u32_e64 s[16:17], v210, v90
	s_nop 1
	v_cndmask_b32_e64 v210, v211, v81, s[16:17]
	v_lshl_add_u32 v210, v210, 2, v79
	ds_add_u32 v210, v214
	v_sub_u32_e32 v210, v194, v91
	v_lshrrev_b32_e32 v211, s2, v194
	v_bitop3_b32 v211, v211, s3, v211 bitop3:0x30
	v_cmp_gt_u32_e64 s[16:17], v210, v90
	s_nop 1
	v_cndmask_b32_e64 v210, v211, v81, s[16:17]
	v_lshl_add_u32 v210, v210, 2, v79
	ds_add_u32 v210, v214
	v_sub_u32_e32 v210, v193, v91
	v_lshrrev_b32_e32 v211, s2, v193
	v_bitop3_b32 v211, v211, s3, v211 bitop3:0x30
	v_cmp_gt_u32_e64 s[16:17], v210, v90
	s_nop 1
	v_cndmask_b32_e64 v210, v211, v81, s[16:17]
	v_lshl_add_u32 v210, v210, 2, v79
	ds_add_u32 v210, v214
	s_cmp_le_u32 m0, 6
	s_cbranch_scc1 .Lsel_pass_skip
	v_sub_u32_e32 v210, v196, v91
	v_lshrrev_b32_e32 v211, s2, v196
	v_bitop3_b32 v211, v211, s3, v211 bitop3:0x30
	v_cmp_gt_u32_e64 s[16:17], v210, v90
	s_nop 1
	v_cndmask_b32_e64 v210, v211, v81, s[16:17]
	v_lshl_add_u32 v210, v210, 2, v79
	ds_add_u32 v210, v214
	v_sub_u32_e32 v210, v195, v91
	v_lshrrev_b32_e32 v211, s2, v195
	v_bitop3_b32 v211, v211, s3, v211 bitop3:0x30
	v_cmp_gt_u32_e64 s[16:17], v210, v90
	s_nop 1
	v_cndmask_b32_e64 v210, v211, v81, s[16:17]
	v_lshl_add_u32 v210, v210, 2, v79
	ds_add_u32 v210, v214
	v_sub_u32_e32 v210, v198, v91
	v_lshrrev_b32_e32 v211, s2, v198
	v_bitop3_b32 v211, v211, s3, v211 bitop3:0x30
	v_cmp_gt_u32_e64 s[16:17], v210, v90
	s_nop 1
	v_cndmask_b32_e64 v210, v211, v81, s[16:17]
	v_lshl_add_u32 v210, v210, 2, v79
	ds_add_u32 v210, v214
	v_sub_u32_e32 v210, v197, v91
	v_lshrrev_b32_e32 v211, s2, v197
	v_bitop3_b32 v211, v211, s3, v211 bitop3:0x30
	v_cmp_gt_u32_e64 s[16:17], v210, v90
	s_nop 1
	v_cndmask_b32_e64 v210, v211, v81, s[16:17]
	v_lshl_add_u32 v210, v210, 2, v79
	ds_add_u32 v210, v214
	v_sub_u32_e32 v210, v200, v91
	v_lshrrev_b32_e32 v211, s2, v200
	v_bitop3_b32 v211, v211, s3, v211 bitop3:0x30
	v_cmp_gt_u32_e64 s[16:17], v210, v90
	s_nop 1
	v_cndmask_b32_e64 v210, v211, v81, s[16:17]
	v_lshl_add_u32 v210, v210, 2, v79
	ds_add_u32 v210, v214
	v_sub_u32_e32 v210, v199, v91
	v_lshrrev_b32_e32 v211, s2, v199
	v_bitop3_b32 v211, v211, s3, v211 bitop3:0x30
	v_cmp_gt_u32_e64 s[16:17], v210, v90
	s_nop 1
	v_cndmask_b32_e64 v210, v211, v81, s[16:17]
	v_lshl_add_u32 v210, v210, 2, v79
	ds_add_u32 v210, v214
	v_sub_u32_e32 v210, v202, v91
	v_lshrrev_b32_e32 v211, s2, v202
	v_bitop3_b32 v211, v211, s3, v211 bitop3:0x30
	v_cmp_gt_u32_e64 s[16:17], v210, v90
	s_nop 1
	v_cndmask_b32_e64 v210, v211, v81, s[16:17]
	v_lshl_add_u32 v210, v210, 2, v79
	ds_add_u32 v210, v214
	v_sub_u32_e32 v210, v201, v91
	v_lshrrev_b32_e32 v211, s2, v201
	v_bitop3_b32 v211, v211, s3, v211 bitop3:0x30
	v_cmp_gt_u32_e64 s[16:17], v210, v90
	s_nop 1
	v_cndmask_b32_e64 v210, v211, v81, s[16:17]
	v_lshl_add_u32 v210, v210, 2, v79
	ds_add_u32 v210, v214
	v_sub_u32_e32 v210, v204, v91
	v_lshrrev_b32_e32 v211, s2, v204
	v_bitop3_b32 v211, v211, s3, v211 bitop3:0x30
	v_cmp_gt_u32_e64 s[16:17], v210, v90
	s_nop 1
	v_cndmask_b32_e64 v210, v211, v81, s[16:17]
	v_lshl_add_u32 v210, v210, 2, v79
	ds_add_u32 v210, v214
	v_sub_u32_e32 v210, v203, v91
	v_lshrrev_b32_e32 v211, s2, v203
	v_bitop3_b32 v211, v211, s3, v211 bitop3:0x30
	v_cmp_gt_u32_e64 s[16:17], v210, v90
	s_nop 1
	v_cndmask_b32_e64 v210, v211, v81, s[16:17]
	v_lshl_add_u32 v210, v210, 2, v79
	ds_add_u32 v210, v214
	v_sub_u32_e32 v210, v206, v91
	v_lshrrev_b32_e32 v211, s2, v206
	v_bitop3_b32 v211, v211, s3, v211 bitop3:0x30
	v_cmp_gt_u32_e64 s[16:17], v210, v90
	s_nop 1
	v_cndmask_b32_e64 v210, v211, v81, s[16:17]
	v_lshl_add_u32 v210, v210, 2, v79
	ds_add_u32 v210, v214
	v_sub_u32_e32 v210, v205, v91
	v_lshrrev_b32_e32 v211, s2, v205
	v_bitop3_b32 v211, v211, s3, v211 bitop3:0x30
	v_cmp_gt_u32_e64 s[16:17], v210, v90
	s_nop 1
	v_cndmask_b32_e64 v210, v211, v81, s[16:17]
	v_lshl_add_u32 v210, v210, 2, v79
	ds_add_u32 v210, v214
	v_sub_u32_e32 v210, v222, v91
	v_lshrrev_b32_e32 v211, s2, v222
	v_bitop3_b32 v211, v211, s3, v211 bitop3:0x30
	v_cmp_gt_u32_e64 s[16:17], v210, v90
	s_nop 1
	v_cndmask_b32_e64 v210, v211, v81, s[16:17]
	v_lshl_add_u32 v210, v210, 2, v79
	ds_add_u32 v210, v214
	v_sub_u32_e32 v210, v207, v91
	v_lshrrev_b32_e32 v211, s2, v207
	v_bitop3_b32 v211, v211, s3, v211 bitop3:0x30
	v_cmp_gt_u32_e64 s[16:17], v210, v90
	s_nop 1
	v_cndmask_b32_e64 v210, v211, v81, s[16:17]
	v_lshl_add_u32 v210, v210, 2, v79
	ds_add_u32 v210, v214
	v_sub_u32_e32 v210, v224, v91
	v_lshrrev_b32_e32 v211, s2, v224
	v_bitop3_b32 v211, v211, s3, v211 bitop3:0x30
	v_cmp_gt_u32_e64 s[16:17], v210, v90
	s_nop 1
	v_cndmask_b32_e64 v210, v211, v81, s[16:17]
	v_lshl_add_u32 v210, v210, 2, v79
	ds_add_u32 v210, v214
	v_sub_u32_e32 v210, v223, v91
	v_lshrrev_b32_e32 v211, s2, v223
	v_bitop3_b32 v211, v211, s3, v211 bitop3:0x30
	v_cmp_gt_u32_e64 s[16:17], v210, v90
	s_nop 1
	v_cndmask_b32_e64 v210, v211, v81, s[16:17]
	v_lshl_add_u32 v210, v210, 2, v79
	ds_add_u32 v210, v214
	s_cmp_le_u32 m0, 7
	s_cbranch_scc1 .Lsel_pass_skip
	v_sub_u32_e32 v210, v226, v91
	v_lshrrev_b32_e32 v211, s2, v226
	v_bitop3_b32 v211, v211, s3, v211 bitop3:0x30
	v_cmp_gt_u32_e64 s[16:17], v210, v90
	s_nop 1
	v_cndmask_b32_e64 v210, v211, v81, s[16:17]
	v_lshl_add_u32 v210, v210, 2, v79
	ds_add_u32 v210, v214
	v_sub_u32_e32 v210, v225, v91
	v_lshrrev_b32_e32 v211, s2, v225
	v_bitop3_b32 v211, v211, s3, v211 bitop3:0x30
	v_cmp_gt_u32_e64 s[16:17], v210, v90
	s_nop 1
	v_cndmask_b32_e64 v210, v211, v81, s[16:17]
	v_lshl_add_u32 v210, v210, 2, v79
	ds_add_u32 v210, v214
	v_sub_u32_e32 v210, v228, v91
	v_lshrrev_b32_e32 v211, s2, v228
	v_bitop3_b32 v211, v211, s3, v211 bitop3:0x30
	v_cmp_gt_u32_e64 s[16:17], v210, v90
	s_nop 1
	v_cndmask_b32_e64 v210, v211, v81, s[16:17]
	v_lshl_add_u32 v210, v210, 2, v79
	ds_add_u32 v210, v214
	v_sub_u32_e32 v210, v227, v91
	v_lshrrev_b32_e32 v211, s2, v227
	v_bitop3_b32 v211, v211, s3, v211 bitop3:0x30
	v_cmp_gt_u32_e64 s[16:17], v210, v90
	s_nop 1
	v_cndmask_b32_e64 v210, v211, v81, s[16:17]
	v_lshl_add_u32 v210, v210, 2, v79
	ds_add_u32 v210, v214
	v_sub_u32_e32 v210, v230, v91
	v_lshrrev_b32_e32 v211, s2, v230
	v_bitop3_b32 v211, v211, s3, v211 bitop3:0x30
	v_cmp_gt_u32_e64 s[16:17], v210, v90
	s_nop 1
	v_cndmask_b32_e64 v210, v211, v81, s[16:17]
	v_lshl_add_u32 v210, v210, 2, v79
	ds_add_u32 v210, v214
	v_sub_u32_e32 v210, v229, v91
	v_lshrrev_b32_e32 v211, s2, v229
	v_bitop3_b32 v211, v211, s3, v211 bitop3:0x30
	v_cmp_gt_u32_e64 s[16:17], v210, v90
	s_nop 1
	v_cndmask_b32_e64 v210, v211, v81, s[16:17]
	v_lshl_add_u32 v210, v210, 2, v79
	ds_add_u32 v210, v214
	v_sub_u32_e32 v210, v232, v91
	v_lshrrev_b32_e32 v211, s2, v232
	v_bitop3_b32 v211, v211, s3, v211 bitop3:0x30
	v_cmp_gt_u32_e64 s[16:17], v210, v90
	s_nop 1
	v_cndmask_b32_e64 v210, v211, v81, s[16:17]
	v_lshl_add_u32 v210, v210, 2, v79
	ds_add_u32 v210, v214
	v_sub_u32_e32 v210, v231, v91
	v_lshrrev_b32_e32 v211, s2, v231
	v_bitop3_b32 v211, v211, s3, v211 bitop3:0x30
	v_cmp_gt_u32_e64 s[16:17], v210, v90
	s_nop 1
	v_cndmask_b32_e64 v210, v211, v81, s[16:17]
	v_lshl_add_u32 v210, v210, 2, v79
	ds_add_u32 v210, v214
	v_sub_u32_e32 v210, v234, v91
	v_lshrrev_b32_e32 v211, s2, v234
	v_bitop3_b32 v211, v211, s3, v211 bitop3:0x30
	v_cmp_gt_u32_e64 s[16:17], v210, v90
	s_nop 1
	v_cndmask_b32_e64 v210, v211, v81, s[16:17]
	v_lshl_add_u32 v210, v210, 2, v79
	ds_add_u32 v210, v214
	v_sub_u32_e32 v210, v233, v91
	v_lshrrev_b32_e32 v211, s2, v233
	v_bitop3_b32 v211, v211, s3, v211 bitop3:0x30
	v_cmp_gt_u32_e64 s[16:17], v210, v90
	s_nop 1
	v_cndmask_b32_e64 v210, v211, v81, s[16:17]
	v_lshl_add_u32 v210, v210, 2, v79
	ds_add_u32 v210, v214
	v_sub_u32_e32 v210, v236, v91
	v_lshrrev_b32_e32 v211, s2, v236
	v_bitop3_b32 v211, v211, s3, v211 bitop3:0x30
	v_cmp_gt_u32_e64 s[16:17], v210, v90
	s_nop 1
	v_cndmask_b32_e64 v210, v211, v81, s[16:17]
	v_lshl_add_u32 v210, v210, 2, v79
	ds_add_u32 v210, v214
	v_sub_u32_e32 v210, v235, v91
	v_lshrrev_b32_e32 v211, s2, v235
	v_bitop3_b32 v211, v211, s3, v211 bitop3:0x30
	v_cmp_gt_u32_e64 s[16:17], v210, v90
	s_nop 1
	v_cndmask_b32_e64 v210, v211, v81, s[16:17]
	v_lshl_add_u32 v210, v210, 2, v79
	ds_add_u32 v210, v214
	v_sub_u32_e32 v210, v238, v91
	v_lshrrev_b32_e32 v211, s2, v238
	v_bitop3_b32 v211, v211, s3, v211 bitop3:0x30
	v_cmp_gt_u32_e64 s[16:17], v210, v90
	s_nop 1
	v_cndmask_b32_e64 v210, v211, v81, s[16:17]
	v_lshl_add_u32 v210, v210, 2, v79
	ds_add_u32 v210, v214
	v_sub_u32_e32 v210, v237, v91
	v_lshrrev_b32_e32 v211, s2, v237
	v_bitop3_b32 v211, v211, s3, v211 bitop3:0x30
	v_cmp_gt_u32_e64 s[16:17], v210, v90
	s_nop 1
	v_cndmask_b32_e64 v210, v211, v81, s[16:17]
	v_lshl_add_u32 v210, v210, 2, v79
	ds_add_u32 v210, v214
	v_sub_u32_e32 v210, v239, v91
	v_lshrrev_b32_e32 v211, s2, v239
	v_bitop3_b32 v211, v211, s3, v211 bitop3:0x30
	v_cmp_gt_u32_e64 s[16:17], v210, v90
	v_sub_u32_e32 v91, v168, v91
	s_nop 0
	v_cndmask_b32_e64 v210, v211, v81, s[16:17]
	v_lshl_add_u32 v210, v210, 2, v79
	ds_add_u32 v210, v214
	v_lshrrev_b32_e32 v210, s2, v168
	v_bitop3_b32 v210, v210, s3, v210 bitop3:0x30
	v_cmp_gt_u32_e64 s[16:17], v91, v90
	v_and_b32_e32 v91, 63, v215
	s_nop 0
	v_cndmask_b32_e64 v90, v210, v81, s[16:17]
	v_lshl_add_u32 v90, v90, 2, v79
	ds_add_u32 v90, v214
	s_branch .Lsel_pass_end
.Lsel_pass_skip:
	v_and_b32_e32 v91, 63, v215
.Lsel_pass_end:
	s_waitcnt lgkmcnt(0)
	ds_read_b128 v[242:245], v83
	ds_read_b128 v[246:249], v83 offset:16
	ds_read_b128 v[250:253], v83 offset:32
	ds_read_b128 v[210:213], v83 offset:48
	v_cmp_ne_u32_e64 s[16:17], 63, v91
	s_waitcnt lgkmcnt(3)
	v_add_u32_e32 v90, v243, v242
	v_add3_u32 v90, v90, v244, v245
	s_waitcnt lgkmcnt(2)
	v_add3_u32 v90, v90, v246, v247
	v_add3_u32 v90, v90, v248, v249
	s_waitcnt lgkmcnt(1)
	v_add3_u32 v90, v90, v250, v251
	ds_read_b128 v[242:245], v83 offset:64
	v_add3_u32 v90, v90, v252, v253
	s_waitcnt lgkmcnt(1)
	v_add3_u32 v90, v90, v210, v211
	v_add3_u32 v90, v90, v212, v213
	ds_read_b128 v[210:213], v83 offset:80
	ds_read_b128 v[246:249], v83 offset:96
	s_waitcnt lgkmcnt(2)
	v_add3_u32 v90, v90, v242, v243
	v_add3_u32 v90, v90, v244, v245
	ds_read_b128 v[242:245], v83 offset:112
	s_waitcnt lgkmcnt(2)
	v_add3_u32 v90, v90, v210, v211
	v_add3_u32 v90, v90, v212, v213
	s_waitcnt lgkmcnt(1)
	v_add3_u32 v90, v90, v246, v247
	v_add3_u32 v90, v90, v248, v249
	s_waitcnt lgkmcnt(0)
	v_add3_u32 v90, v90, v242, v243
	v_addc_co_u32_e64 v210, s[16:17], 0, v215, s[16:17]
	v_add3_u32 v90, v90, v244, v245
	v_lshlrev_b32_e32 v210, 2, v210
	ds_bpermute_b32 v210, v210, v90
	v_cmp_gt_u32_e64 s[16:17], 62, v91
	s_waitcnt lgkmcnt(0)
	v_cndmask_b32_e64 v210, v210, 0, s[4:5]
	v_cndmask_b32_e64 v211, 0, 2, s[16:17]
	v_add_u32_e32 v210, v210, v90
	v_add_lshl_u32 v211, v211, v215, 2
	ds_bpermute_b32 v211, v211, v210
	v_cmp_gt_u32_e64 s[16:17], 60, v91
	s_waitcnt lgkmcnt(0)
	v_cndmask_b32_e64 v211, 0, v211, s[6:7]
	v_add_u32_e32 v210, v211, v210
	v_cndmask_b32_e64 v211, 0, 4, s[16:17]
	v_add_lshl_u32 v211, v211, v215, 2
	ds_bpermute_b32 v211, v211, v210
	v_cmp_gt_u32_e64 s[16:17], 56, v91
	s_waitcnt lgkmcnt(0)
	v_cndmask_b32_e64 v211, 0, v211, s[8:9]
	v_add_u32_e32 v210, v211, v210
	v_cndmask_b32_e64 v211, 0, 8, s[16:17]
	v_add_lshl_u32 v211, v211, v215, 2
	ds_bpermute_b32 v211, v211, v210
	v_cmp_gt_u32_e64 s[16:17], 48, v91
	s_waitcnt lgkmcnt(0)
	v_cndmask_b32_e64 v211, 0, v211, s[10:11]
	v_cndmask_b32_e64 v91, 0, 16, s[16:17]
	v_add_u32_e32 v210, v211, v210
	v_add_lshl_u32 v91, v91, v215, 2
	ds_bpermute_b32 v91, v91, v210
	s_waitcnt lgkmcnt(0)
	v_cndmask_b32_e64 v91, 0, v91, s[12:13]
	v_add_u32_e32 v91, v91, v210
	v_lshl_or_b32 v210, v215, 2, v219
	ds_bpermute_b32 v210, v210, v91
	s_waitcnt lgkmcnt(0)
	v_cndmask_b32_e64 v210, 0, v210, s[14:15]
	v_add_u32_e32 v91, v210, v91
	v_sub_u32_e32 v244, v91, v90
	v_cmp_lt_i32_e64 s[16:17], v244, v240
	v_cmp_ge_i32_e64 s[18:19], v91, v240
	s_and_b64 s[2:3], s[18:19], s[16:17]
	v_mov_b32_e32 v91, 0
	v_mov_b32_e32 v90, 0
	s_and_saveexec_b64 s[18:19], s[2:3]
	s_cbranch_execz .LBB0_676
	s_mov_b64 s[16:17], 0
	v_mov_b32_e32 v90, 0
	s_movk_i32 s34, 0x7c
	v_mov_b32_e32 v242, v112
	v_mov_b32_e32 v91, 0
	v_mov_b32_e32 v241, 0

.LBB0_695:
	s_andn2_saveexec_b64 s[22:23], s[2:3]
	s_cbranch_execz .LBB0_671
	ds_read_b32 v87, v6 offset:36864
	v_mov_b32_e32 v88, v0
	v_mov_b32_e32 v89, v0
	v_cmp_ne_u32_e64 s[20:21], 0, v114
	v_mov_b32_e32 v92, v0
	s_waitcnt lgkmcnt(0)
	v_cmp_ge_u32_e64 s[16:17], v87, v153
	v_cmp_ne_u32_e64 s[18:19], 0, v87
	s_and_b64 s[2:3], s[16:17], s[18:19]
	v_cndmask_b32_e64 v87, 0, 1, s[2:3]
	v_cmp_ne_u32_e64 s[16:17], 0, v87
	s_nop 1
	v_writelane_b32 v88, s16, 0
	v_writelane_b32 v89, s17, 0
	ds_read_b32 v87, v6 offset:37120
	v_mov_b32_e32 v93, v0
	s_waitcnt lgkmcnt(0)
	v_cmp_ge_u32_e64 s[16:17], v87, v153
	v_cmp_ne_u32_e64 s[18:19], 0, v87
	s_and_b64 s[2:3], s[16:17], s[18:19]
	v_cndmask_b32_e64 v87, 0, 1, s[2:3]
	v_cmp_ne_u32_e64 s[16:17], 0, v87
	s_nop 1
	v_writelane_b32 v88, s16, 1
	v_writelane_b32 v89, s17, 1
	ds_read_b32 v87, v6 offset:37376
	s_waitcnt lgkmcnt(0)
	v_cmp_ge_u32_e64 s[16:17], v87, v153
	v_cmp_ne_u32_e64 s[18:19], 0, v87
	s_and_b64 s[2:3], s[16:17], s[18:19]
	v_cndmask_b32_e64 v87, 0, 1, s[2:3]
	v_cmp_ne_u32_e64 s[16:17], 0, v87
	s_nop 1
	v_writelane_b32 v88, s16, 2
	v_writelane_b32 v89, s17, 2
	ds_read_b32 v87, v6 offset:37632
	s_waitcnt lgkmcnt(0)
	v_cmp_ge_u32_e64 s[16:17], v87, v153
	v_cmp_ne_u32_e64 s[18:19], 0, v87
	s_and_b64 s[2:3], s[16:17], s[18:19]
	v_cndmask_b32_e64 v87, 0, 1, s[2:3]
	v_cmp_ne_u32_e64 s[16:17], 0, v87
	s_nop 1
	v_writelane_b32 v88, s16, 3
	v_writelane_b32 v89, s17, 3
	ds_read_b32 v87, v6 offset:37888
	s_waitcnt lgkmcnt(0)
	v_cmp_ge_u32_e64 s[16:17], v87, v153
	v_cmp_ne_u32_e64 s[18:19], 0, v87
	s_and_b64 s[2:3], s[16:17], s[18:19]
	v_cndmask_b32_e64 v87, 0, 1, s[2:3]
	v_cmp_ne_u32_e64 s[16:17], 0, v87
	s_nop 1
	v_writelane_b32 v88, s16, 4
	v_writelane_b32 v89, s17, 4
	ds_read_b32 v87, v6 offset:38144
	s_waitcnt lgkmcnt(0)
	v_cmp_ge_u32_e64 s[16:17], v87, v153
	v_cmp_ne_u32_e64 s[18:19], 0, v87
	s_and_b64 s[2:3], s[16:17], s[18:19]
	v_cndmask_b32_e64 v87, 0, 1, s[2:3]
	v_cmp_ne_u32_e64 s[16:17], 0, v87
	s_nop 1
	v_writelane_b32 v88, s16, 5
	v_writelane_b32 v89, s17, 5
	ds_read_b32 v87, v6 offset:38400
	s_waitcnt lgkmcnt(0)
	v_cmp_ge_u32_e64 s[16:17], v87, v153
	v_cmp_ne_u32_e64 s[18:19], 0, v87
	s_and_b64 s[2:3], s[16:17], s[18:19]
	v_cndmask_b32_e64 v87, 0, 1, s[2:3]
	v_cmp_ne_u32_e64 s[16:17], 0, v87
	s_nop 1
	v_writelane_b32 v88, s16, 6
	v_writelane_b32 v89, s17, 6
	ds_read_b32 v87, v6 offset:38656
	s_waitcnt lgkmcnt(0)
	v_cmp_ge_u32_e64 s[16:17], v87, v153
	v_cmp_ne_u32_e64 s[18:19], 0, v87
	s_and_b64 s[2:3], s[16:17], s[18:19]
	v_cndmask_b32_e64 v87, 0, 1, s[2:3]
	v_cmp_ne_u32_e64 s[16:17], 0, v87
	s_nop 1
	v_writelane_b32 v88, s16, 7
	v_writelane_b32 v89, s17, 7
	ds_read_b32 v87, v6 offset:38912
	s_waitcnt lgkmcnt(0)
	v_cmp_ge_u32_e64 s[16:17], v87, v153
	v_cmp_ne_u32_e64 s[18:19], 0, v87
	s_and_b64 s[2:3], s[16:17], s[18:19]
	v_cndmask_b32_e64 v87, 0, 1, s[2:3]
	v_cmp_ne_u32_e64 s[16:17], 0, v87
	s_nop 1
	v_writelane_b32 v88, s16, 8
	v_writelane_b32 v89, s17, 8
	ds_read_b32 v87, v6 offset:39168
	s_waitcnt lgkmcnt(0)
	v_cmp_ge_u32_e64 s[16:17], v87, v153
	v_cmp_ne_u32_e64 s[18:19], 0, v87
	s_and_b64 s[2:3], s[16:17], s[18:19]
	v_cndmask_b32_e64 v87, 0, 1, s[2:3]
	v_cmp_ne_u32_e64 s[16:17], 0, v87
	s_nop 1
	v_writelane_b32 v88, s16, 9
	v_writelane_b32 v89, s17, 9
	ds_read_b32 v87, v6 offset:39424
	s_waitcnt lgkmcnt(0)
	v_cmp_ge_u32_e64 s[16:17], v87, v153
	v_cmp_ne_u32_e64 s[18:19], 0, v87
	s_and_b64 s[2:3], s[16:17], s[18:19]
	v_cndmask_b32_e64 v87, 0, 1, s[2:3]
	v_cmp_ne_u32_e64 s[16:17], 0, v87
	s_nop 1
	v_writelane_b32 v88, s16, 10
	v_writelane_b32 v89, s17, 10
	ds_read_b32 v87, v6 offset:39680
	s_waitcnt lgkmcnt(0)
	v_cmp_ge_u32_e64 s[16:17], v87, v153
	v_cmp_ne_u32_e64 s[18:19], 0, v87
	s_and_b64 s[2:3], s[16:17], s[18:19]
	v_cndmask_b32_e64 v87, 0, 1, s[2:3]
	v_cmp_ne_u32_e64 s[16:17], 0, v87
	s_nop 1
	v_writelane_b32 v88, s16, 11
	v_writelane_b32 v89, s17, 11
	ds_read_b32 v87, v6 offset:39936
	s_waitcnt lgkmcnt(0)
	v_cmp_ge_u32_e64 s[16:17], v87, v153
	v_cmp_ne_u32_e64 s[18:19], 0, v87
	s_and_b64 s[2:3], s[16:17], s[18:19]
	v_cndmask_b32_e64 v87, 0, 1, s[2:3]
	v_cmp_ne_u32_e64 s[16:17], 0, v87
	s_nop 1
	v_writelane_b32 v88, s16, 12
	v_writelane_b32 v89, s17, 12
	ds_read_b32 v87, v6 offset:40192
	s_waitcnt lgkmcnt(0)
	v_cmp_ge_u32_e64 s[16:17], v87, v153
	v_cmp_ne_u32_e64 s[18:19], 0, v87
	s_and_b64 s[2:3], s[16:17], s[18:19]
	v_cndmask_b32_e64 v87, 0, 1, s[2:3]
	v_cmp_ne_u32_e64 s[16:17], 0, v87
	s_nop 1
	v_writelane_b32 v88, s16, 13
	v_writelane_b32 v89, s17, 13
	ds_read_b32 v87, v6 offset:40448
	s_waitcnt lgkmcnt(0)
	v_cmp_ge_u32_e64 s[16:17], v87, v153
	v_cmp_ne_u32_e64 s[18:19], 0, v87
	s_and_b64 s[2:3], s[16:17], s[18:19]
	v_cndmask_b32_e64 v87, 0, 1, s[2:3]
	v_cmp_ne_u32_e64 s[16:17], 0, v87
	s_nop 1
	v_writelane_b32 v88, s16, 14
	v_writelane_b32 v89, s17, 14
	ds_read_b32 v87, v6 offset:40704
	s_waitcnt lgkmcnt(0)
	v_cmp_ge_u32_e64 s[16:17], v87, v153
	v_cmp_ne_u32_e64 s[18:19], 0, v87
	s_and_b64 s[2:3], s[16:17], s[18:19]
	v_cndmask_b32_e64 v87, 0, 1, s[2:3]
	v_cmp_ne_u32_e64 s[16:17], 0, v87
	s_nop 1
	v_writelane_b32 v88, s16, 15
	v_writelane_b32 v89, s17, 15
	v_cmp_ge_u32_e64 s[16:17], v114, v153
	s_and_b64 s[2:3], s[20:21], s[16:17]
	v_cndmask_b32_e64 v87, 0, 1, s[2:3]
	v_cmp_ne_u32_e64 s[16:17], 0, v87
	v_cmp_ne_u32_e64 s[18:19], 0, v113
	s_nop 1
	v_writelane_b32 v88, s16, 16
	v_writelane_b32 v89, s17, 16
	v_cmp_ge_u32_e64 s[16:17], v113, v153
	s_and_b64 s[2:3], s[18:19], s[16:17]
	v_cndmask_b32_e64 v87, 0, 1, s[2:3]
	v_cmp_ne_u32_e64 s[16:17], 0, v87
	s_nop 1
	v_writelane_b32 v88, s16, 17
	v_writelane_b32 v89, s17, 17
	s_cmp_le_u32 m0, 1
	s_cbranch_scc1 .Lsel_fin_tail
	v_cmp_ge_u32_e64 s[16:17], v116, v153
	v_cmp_ne_u32_e64 s[20:21], 0, v116
	s_and_b64 s[2:3], s[20:21], s[16:17]
	v_cndmask_b32_e64 v87, 0, 1, s[2:3]
	v_cmp_ne_u32_e64 s[16:17], 0, v87
	v_cmp_ne_u32_e64 s[18:19], 0, v115
	s_nop 1
	v_writelane_b32 v88, s16, 18
	v_writelane_b32 v89, s17, 18
	v_cmp_ge_u32_e64 s[16:17], v115, v153
	s_and_b64 s[2:3], s[18:19], s[16:17]
	v_cndmask_b32_e64 v87, 0, 1, s[2:3]
	v_cmp_ne_u32_e64 s[16:17], 0, v87
	s_nop 1
	v_writelane_b32 v88, s16, 19
	v_writelane_b32 v89, s17, 19
	v_cmp_ge_u32_e64 s[16:17], v118, v153
	v_cmp_ne_u32_e64 s[20:21], 0, v118
	s_and_b64 s[2:3], s[20:21], s[16:17]
	v_cndmask_b32_e64 v87, 0, 1, s[2:3]
	v_cmp_ne_u32_e64 s[16:17], 0, v87
	v_cmp_ne_u32_e64 s[18:19], 0, v117
	s_nop 1
	v_writelane_b32 v88, s16, 20
	v_writelane_b32 v89, s17, 20
	v_cmp_ge_u32_e64 s[16:17], v117, v153
	s_and_b64 s[2:3], s[18:19], s[16:17]
	v_cndmask_b32_e64 v87, 0, 1, s[2:3]
	v_cmp_ne_u32_e64 s[16:17], 0, v87
	s_nop 1
	v_writelane_b32 v88, s16, 21
	v_writelane_b32 v89, s17, 21
	v_cmp_ge_u32_e64 s[16:17], v120, v153
	v_cmp_ne_u32_e64 s[20:21], 0, v120
	s_and_b64 s[2:3], s[20:21], s[16:17]
	v_cndmask_b32_e64 v87, 0, 1, s[2:3]
	v_cmp_ne_u32_e64 s[16:17], 0, v87
	v_cmp_ne_u32_e64 s[18:19], 0, v119
	s_nop 1
	v_writelane_b32 v88, s16, 22
	v_writelane_b32 v89, s17, 22
	v_cmp_ge_u32_e64 s[16:17], v119, v153
	s_and_b64 s[2:3], s[18:19], s[16:17]
	v_cndmask_b32_e64 v87, 0, 1, s[2:3]
	v_cmp_ne_u32_e64 s[16:17], 0, v87
	s_nop 1
	v_writelane_b32 v88, s16, 23
	v_writelane_b32 v89, s17, 23
	v_cmp_ge_u32_e64 s[16:17], v122, v153
	v_cmp_ne_u32_e64 s[20:21], 0, v122
	s_and_b64 s[2:3], s[20:21], s[16:17]
	v_cndmask_b32_e64 v87, 0, 1, s[2:3]
	v_cmp_ne_u32_e64 s[16:17], 0, v87
	v_cmp_ne_u32_e64 s[18:19], 0, v121
	s_nop 1
	v_writelane_b32 v88, s16, 24
	v_writelane_b32 v89, s17, 24
	v_cmp_ge_u32_e64 s[16:17], v121, v153
	s_and_b64 s[2:3], s[18:19], s[16:17]
	v_cndmask_b32_e64 v87, 0, 1, s[2:3]
	v_cmp_ne_u32_e64 s[16:17], 0, v87
	s_nop 1
	v_writelane_b32 v88, s16, 25
	v_writelane_b32 v89, s17, 25
	v_cmp_ge_u32_e64 s[16:17], v124, v153
	v_cmp_ne_u32_e64 s[20:21], 0, v124
	s_and_b64 s[2:3], s[20:21], s[16:17]
	v_cndmask_b32_e64 v87, 0, 1, s[2:3]
	v_cmp_ne_u32_e64 s[16:17], 0, v87
	v_cmp_ne_u32_e64 s[18:19], 0, v123
	s_nop 1
	v_writelane_b32 v88, s16, 26
	v_writelane_b32 v89, s17, 26
	v_cmp_ge_u32_e64 s[16:17], v123, v153
	s_and_b64 s[2:3], s[18:19], s[16:17]
	v_cndmask_b32_e64 v87, 0, 1, s[2:3]
	v_cmp_ne_u32_e64 s[16:17], 0, v87
	s_nop 1
	v_writelane_b32 v88, s16, 27
	v_writelane_b32 v89, s17, 27
	v_cmp_ge_u32_e64 s[16:17], v126, v153
	v_cmp_ne_u32_e64 s[20:21], 0, v126
	s_and_b64 s[2:3], s[20:21], s[16:17]
	v_cndmask_b32_e64 v87, 0, 1, s[2:3]
	v_cmp_ne_u32_e64 s[16:17], 0, v87
	v_cmp_ne_u32_e64 s[18:19], 0, v125
	s_nop 1
	v_writelane_b32 v88, s16, 28
	v_writelane_b32 v89, s17, 28
	v_cmp_ge_u32_e64 s[16:17], v125, v153
	s_and_b64 s[2:3], s[18:19], s[16:17]
	v_cndmask_b32_e64 v87, 0, 1, s[2:3]
	v_cmp_ne_u32_e64 s[16:17], 0, v87
	s_nop 1
	v_writelane_b32 v88, s16, 29
	v_writelane_b32 v89, s17, 29
	v_cmp_ge_u32_e64 s[16:17], v128, v153
	v_cmp_ne_u32_e64 s[20:21], 0, v128
	s_and_b64 s[2:3], s[20:21], s[16:17]
	v_cndmask_b32_e64 v87, 0, 1, s[2:3]
	v_cmp_ne_u32_e64 s[16:17], 0, v87
	v_cmp_ne_u32_e64 s[18:19], 0, v127
	s_nop 1
	v_writelane_b32 v88, s16, 30
	v_writelane_b32 v89, s17, 30
	v_cmp_ge_u32_e64 s[16:17], v127, v153
	s_and_b64 s[2:3], s[18:19], s[16:17]
	v_cndmask_b32_e64 v87, 0, 1, s[2:3]
	v_cmp_ne_u32_e64 s[16:17], 0, v87
	s_nop 1
	v_writelane_b32 v88, s16, 31
	v_writelane_b32 v89, s17, 31
	s_cmp_le_u32 m0, 2
	s_cbranch_scc1 .Lsel_fin_tail
	v_cmp_ge_u32_e64 s[16:17], v130, v153
	v_cmp_ne_u32_e64 s[20:21], 0, v130
	s_and_b64 s[2:3], s[20:21], s[16:17]
	v_cndmask_b32_e64 v87, 0, 1, s[2:3]
	v_cmp_ne_u32_e64 s[16:17], 0, v87
	v_cmp_ne_u32_e64 s[18:19], 0, v129
	s_nop 1
	v_writelane_b32 v88, s16, 32
	v_writelane_b32 v89, s17, 32
	v_cmp_ge_u32_e64 s[16:17], v129, v153
	s_and_b64 s[2:3], s[18:19], s[16:17]
	v_cndmask_b32_e64 v87, 0, 1, s[2:3]
	v_cmp_ne_u32_e64 s[16:17], 0, v87
	s_nop 1
	v_writelane_b32 v88, s16, 33
	v_writelane_b32 v89, s17, 33
	v_cmp_ge_u32_e64 s[16:17], v132, v153
	v_cmp_ne_u32_e64 s[20:21], 0, v132
	s_and_b64 s[2:3], s[20:21], s[16:17]
	v_cndmask_b32_e64 v87, 0, 1, s[2:3]
	v_cmp_ne_u32_e64 s[16:17], 0, v87
	v_cmp_ne_u32_e64 s[18:19], 0, v131
	s_nop 1
	v_writelane_b32 v88, s16, 34
	v_writelane_b32 v89, s17, 34
	v_cmp_ge_u32_e64 s[16:17], v131, v153
	s_and_b64 s[2:3], s[18:19], s[16:17]
	v_cndmask_b32_e64 v87, 0, 1, s[2:3]
	v_cmp_ne_u32_e64 s[16:17], 0, v87
	s_nop 1
	v_writelane_b32 v88, s16, 35
	v_writelane_b32 v89, s17, 35
	v_cmp_ge_u32_e64 s[16:17], v134, v153
	v_cmp_ne_u32_e64 s[20:21], 0, v134
	s_and_b64 s[2:3], s[20:21], s[16:17]
	v_cndmask_b32_e64 v87, 0, 1, s[2:3]
	v_cmp_ne_u32_e64 s[16:17], 0, v87
	v_cmp_ne_u32_e64 s[18:19], 0, v133
	s_nop 1
	v_writelane_b32 v88, s16, 36
	v_writelane_b32 v89, s17, 36
	v_cmp_ge_u32_e64 s[16:17], v133, v153
	s_and_b64 s[2:3], s[18:19], s[16:17]
	v_cndmask_b32_e64 v87, 0, 1, s[2:3]
	v_cmp_ne_u32_e64 s[16:17], 0, v87
	s_nop 1
	v_writelane_b32 v88, s16, 37
	v_writelane_b32 v89, s17, 37
	v_cmp_ge_u32_e64 s[16:17], v136, v153
	v_cmp_ne_u32_e64 s[20:21], 0, v136
	s_and_b64 s[2:3], s[20:21], s[16:17]
	v_cndmask_b32_e64 v87, 0, 1, s[2:3]
	v_cmp_ne_u32_e64 s[16:17], 0, v87
	v_cmp_ne_u32_e64 s[18:19], 0, v135
	s_nop 1
	v_writelane_b32 v88, s16, 38
	v_writelane_b32 v89, s17, 38
	v_cmp_ge_u32_e64 s[16:17], v135, v153
	s_and_b64 s[2:3], s[18:19], s[16:17]
	v_cndmask_b32_e64 v87, 0, 1, s[2:3]
	v_cmp_ne_u32_e64 s[16:17], 0, v87
	s_nop 1
	v_writelane_b32 v88, s16, 39
	v_writelane_b32 v89, s17, 39
	v_cmp_ge_u32_e64 s[16:17], v138, v153
	v_cmp_ne_u32_e64 s[20:21], 0, v138
	s_and_b64 s[2:3], s[20:21], s[16:17]
	v_cndmask_b32_e64 v87, 0, 1, s[2:3]
	v_cmp_ne_u32_e64 s[16:17], 0, v87
	v_cmp_ne_u32_e64 s[18:19], 0, v137
	s_nop 1
	v_writelane_b32 v88, s16, 40
	v_writelane_b32 v89, s17, 40
	v_cmp_ge_u32_e64 s[16:17], v137, v153
	s_and_b64 s[2:3], s[18:19], s[16:17]
	v_cndmask_b32_e64 v87, 0, 1, s[2:3]
	v_cmp_ne_u32_e64 s[16:17], 0, v87
	s_nop 1
	v_writelane_b32 v88, s16, 41
	v_writelane_b32 v89, s17, 41
	v_cmp_ge_u32_e64 s[16:17], v140, v153
	v_cmp_ne_u32_e64 s[20:21], 0, v140
	s_and_b64 s[2:3], s[20:21], s[16:17]
	v_cndmask_b32_e64 v87, 0, 1, s[2:3]
	v_cmp_ne_u32_e64 s[16:17], 0, v87
	v_cmp_ne_u32_e64 s[18:19], 0, v139
	s_nop 1
	v_writelane_b32 v88, s16, 42
	v_writelane_b32 v89, s17, 42
	v_cmp_ge_u32_e64 s[16:17], v139, v153
	s_and_b64 s[2:3], s[18:19], s[16:17]
	v_cndmask_b32_e64 v87, 0, 1, s[2:3]
	v_cmp_ne_u32_e64 s[16:17], 0, v87
	s_nop 1
	v_writelane_b32 v88, s16, 43
	v_writelane_b32 v89, s17, 43
	v_cmp_ge_u32_e64 s[16:17], v142, v153
	v_cmp_ne_u32_e64 s[20:21], 0, v142
	s_and_b64 s[2:3], s[20:21], s[16:17]
	v_cndmask_b32_e64 v87, 0, 1, s[2:3]
	v_cmp_ne_u32_e64 s[16:17], 0, v87
	v_cmp_ne_u32_e64 s[18:19], 0, v141
	s_nop 1
	v_writelane_b32 v88, s16, 44
	v_writelane_b32 v89, s17, 44
	v_cmp_ge_u32_e64 s[16:17], v141, v153
	s_and_b64 s[2:3], s[18:19], s[16:17]
	v_cndmask_b32_e64 v87, 0, 1, s[2:3]
	v_cmp_ne_u32_e64 s[16:17], 0, v87
	s_nop 1
	v_writelane_b32 v88, s16, 45
	v_writelane_b32 v89, s17, 45
	v_cmp_ge_u32_e64 s[16:17], v144, v153
	v_cmp_ne_u32_e64 s[20:21], 0, v144
	s_and_b64 s[2:3], s[20:21], s[16:17]
	v_cndmask_b32_e64 v87, 0, 1, s[2:3]
	v_cmp_ne_u32_e64 s[16:17], 0, v87
	v_cmp_ne_u32_e64 s[18:19], 0, v143
	s_nop 1
	v_writelane_b32 v88, s16, 46
	v_writelane_b32 v89, s17, 46
	v_cmp_ge_u32_e64 s[16:17], v143, v153
	s_and_b64 s[2:3], s[18:19], s[16:17]
	v_cndmask_b32_e64 v87, 0, 1, s[2:3]
	v_cmp_ne_u32_e64 s[16:17], 0, v87
	s_nop 1
	v_writelane_b32 v88, s16, 47
	v_writelane_b32 v89, s17, 47
	s_cmp_le_u32 m0, 3
	s_cbranch_scc1 .Lsel_fin_tail
	v_cmp_ge_u32_e64 s[16:17], v146, v153
	v_cmp_ne_u32_e64 s[20:21], 0, v146
	s_and_b64 s[2:3], s[20:21], s[16:17]
	v_cndmask_b32_e64 v87, 0, 1, s[2:3]
	v_cmp_ne_u32_e64 s[16:17], 0, v87
	v_cmp_ne_u32_e64 s[18:19], 0, v145
	s_nop 1
	v_writelane_b32 v88, s16, 48
	v_writelane_b32 v89, s17, 48
	v_cmp_ge_u32_e64 s[16:17], v145, v153
	s_and_b64 s[2:3], s[18:19], s[16:17]
	v_cndmask_b32_e64 v87, 0, 1, s[2:3]
	v_cmp_ne_u32_e64 s[16:17], 0, v87
	s_nop 1
	v_writelane_b32 v88, s16, 49
	v_writelane_b32 v89, s17, 49
	v_cmp_ge_u32_e64 s[16:17], v148, v153
	v_cmp_ne_u32_e64 s[20:21], 0, v148
	s_and_b64 s[2:3], s[20:21], s[16:17]
	v_cndmask_b32_e64 v87, 0, 1, s[2:3]
	v_cmp_ne_u32_e64 s[16:17], 0, v87
	v_cmp_ne_u32_e64 s[18:19], 0, v147
	s_nop 1
	v_writelane_b32 v88, s16, 50
	v_writelane_b32 v89, s17, 50
	v_cmp_ge_u32_e64 s[16:17], v147, v153
	s_and_b64 s[2:3], s[18:19], s[16:17]
	v_cndmask_b32_e64 v87, 0, 1, s[2:3]
	v_cmp_ne_u32_e64 s[16:17], 0, v87
	s_nop 1
	v_writelane_b32 v88, s16, 51
	v_writelane_b32 v89, s17, 51
	v_cmp_ge_u32_e64 s[16:17], v150, v153
	v_cmp_ne_u32_e64 s[20:21], 0, v150
	s_and_b64 s[2:3], s[20:21], s[16:17]
	v_cndmask_b32_e64 v87, 0, 1, s[2:3]
	v_cmp_ne_u32_e64 s[16:17], 0, v87
	v_cmp_ne_u32_e64 s[18:19], 0, v149
	s_nop 1
	v_writelane_b32 v88, s16, 52
	v_writelane_b32 v89, s17, 52
	v_cmp_ge_u32_e64 s[16:17], v149, v153
	s_and_b64 s[2:3], s[18:19], s[16:17]
	v_cndmask_b32_e64 v87, 0, 1, s[2:3]
	v_cmp_ne_u32_e64 s[16:17], 0, v87
	s_nop 1
	v_writelane_b32 v88, s16, 53
	v_writelane_b32 v89, s17, 53
	v_cmp_ge_u32_e64 s[16:17], v152, v153
	v_cmp_ne_u32_e64 s[20:21], 0, v152
	s_and_b64 s[2:3], s[20:21], s[16:17]
	v_cndmask_b32_e64 v87, 0, 1, s[2:3]
	v_cmp_ne_u32_e64 s[16:17], 0, v87
	v_cmp_ne_u32_e64 s[18:19], 0, v151
	s_nop 1
	v_writelane_b32 v88, s16, 54
	v_writelane_b32 v89, s17, 54
	v_cmp_ge_u32_e64 s[16:17], v151, v153
	s_and_b64 s[2:3], s[18:19], s[16:17]
	v_cndmask_b32_e64 v87, 0, 1, s[2:3]
	v_cmp_ne_u32_e64 s[16:17], 0, v87
	s_nop 1
	v_writelane_b32 v88, s16, 55
	v_writelane_b32 v89, s17, 55
	v_cmp_ge_u32_e64 s[16:17], v155, v153
	v_cmp_ne_u32_e64 s[20:21], 0, v155
	s_and_b64 s[2:3], s[20:21], s[16:17]
	v_cndmask_b32_e64 v87, 0, 1, s[2:3]
	v_cmp_ne_u32_e64 s[16:17], 0, v87
	v_cmp_ne_u32_e64 s[18:19], 0, v154
	s_nop 1
	v_writelane_b32 v88, s16, 56
	v_writelane_b32 v89, s17, 56
	v_cmp_ge_u32_e64 s[16:17], v154, v153
	s_and_b64 s[2:3], s[18:19], s[16:17]
	v_cndmask_b32_e64 v87, 0, 1, s[2:3]
	v_cmp_ne_u32_e64 s[16:17], 0, v87
	s_nop 1
	v_writelane_b32 v88, s16, 57
	v_writelane_b32 v89, s17, 57
	v_cmp_ge_u32_e64 s[16:17], v157, v153
	v_cmp_ne_u32_e64 s[20:21], 0, v157
	s_and_b64 s[2:3], s[20:21], s[16:17]
	v_cndmask_b32_e64 v87, 0, 1, s[2:3]
	v_cmp_ne_u32_e64 s[16:17], 0, v87
	v_cmp_ne_u32_e64 s[18:19], 0, v156
	s_nop 1
	v_writelane_b32 v88, s16, 58
	v_writelane_b32 v89, s17, 58
	v_cmp_ge_u32_e64 s[16:17], v156, v153
	s_and_b64 s[2:3], s[18:19], s[16:17]
	v_cndmask_b32_e64 v87, 0, 1, s[2:3]
	v_cmp_ne_u32_e64 s[16:17], 0, v87
	s_nop 1
	v_writelane_b32 v88, s16, 59
	v_writelane_b32 v89, s17, 59
	v_cmp_ge_u32_e64 s[16:17], v159, v153
	v_cmp_ne_u32_e64 s[20:21], 0, v159
	s_and_b64 s[2:3], s[20:21], s[16:17]
	v_cndmask_b32_e64 v87, 0, 1, s[2:3]
	v_cmp_ne_u32_e64 s[16:17], 0, v87
	v_cmp_ne_u32_e64 s[18:19], 0, v158
	s_nop 1
	v_writelane_b32 v88, s16, 60
	v_writelane_b32 v89, s17, 60
	v_cmp_ge_u32_e64 s[16:17], v158, v153
	s_and_b64 s[2:3], s[18:19], s[16:17]
	v_cndmask_b32_e64 v87, 0, 1, s[2:3]
	v_cmp_ne_u32_e64 s[16:17], 0, v87
	s_nop 1
	v_writelane_b32 v88, s16, 61
	v_writelane_b32 v89, s17, 61
	v_cmp_ge_u32_e64 s[16:17], v161, v153
	v_cmp_ne_u32_e64 s[20:21], 0, v161
	s_and_b64 s[2:3], s[20:21], s[16:17]
	v_cndmask_b32_e64 v87, 0, 1, s[2:3]
	v_cmp_ne_u32_e64 s[16:17], 0, v87
	v_cmp_ne_u32_e64 s[18:19], 0, v160
	s_nop 1
	v_writelane_b32 v88, s16, 62
	v_writelane_b32 v89, s17, 62
	v_cmp_ge_u32_e64 s[16:17], v160, v153
	s_and_b64 s[2:3], s[18:19], s[16:17]
	v_cndmask_b32_e64 v87, 0, 1, s[2:3]
	v_cmp_ne_u32_e64 s[16:17], 0, v87
	s_nop 1
	v_writelane_b32 v88, s16, 63
	v_writelane_b32 v89, s17, 63
	s_cmp_le_u32 m0, 4
	s_cbranch_scc1 .Lsel_fin_tail
	v_cmp_ge_u32_e64 s[16:17], v163, v153
	v_cmp_ne_u32_e64 s[20:21], 0, v163
	s_and_b64 s[2:3], s[20:21], s[16:17]
	v_cndmask_b32_e64 v87, 0, 1, s[2:3]
	v_cmp_ne_u32_e64 s[16:17], 0, v87
	v_cmp_ne_u32_e64 s[18:19], 0, v162
	s_nop 1
	v_writelane_b32 v92, s16, 0
	v_writelane_b32 v93, s17, 0
	v_cmp_ge_u32_e64 s[16:17], v162, v153
	s_and_b64 s[2:3], s[18:19], s[16:17]
	v_cndmask_b32_e64 v87, 0, 1, s[2:3]
	v_cmp_ne_u32_e64 s[16:17], 0, v87
	s_nop 1
	v_writelane_b32 v92, s16, 1
	v_writelane_b32 v93, s17, 1
	v_cmp_ge_u32_e64 s[16:17], v165, v153
	v_cmp_ne_u32_e64 s[20:21], 0, v165
	s_and_b64 s[2:3], s[20:21], s[16:17]
	v_cndmask_b32_e64 v87, 0, 1, s[2:3]
	v_cmp_ne_u32_e64 s[16:17], 0, v87
	v_cmp_ne_u32_e64 s[18:19], 0, v164
	s_nop 1
	v_writelane_b32 v92, s16, 2
	v_writelane_b32 v93, s17, 2
	v_cmp_ge_u32_e64 s[16:17], v164, v153
	s_and_b64 s[2:3], s[18:19], s[16:17]
	v_cndmask_b32_e64 v87, 0, 1, s[2:3]
	v_cmp_ne_u32_e64 s[16:17], 0, v87
	s_nop 1
	v_writelane_b32 v92, s16, 3
	v_writelane_b32 v93, s17, 3
	v_cmp_ge_u32_e64 s[16:17], v167, v153
	v_cmp_ne_u32_e64 s[20:21], 0, v167
	s_and_b64 s[2:3], s[20:21], s[16:17]
	v_cndmask_b32_e64 v87, 0, 1, s[2:3]
	v_cmp_ne_u32_e64 s[16:17], 0, v87
	v_cmp_ne_u32_e64 s[18:19], 0, v166
	s_nop 1
	v_writelane_b32 v92, s16, 4
	v_writelane_b32 v93, s17, 4
	v_cmp_ge_u32_e64 s[16:17], v166, v153
	s_and_b64 s[2:3], s[18:19], s[16:17]
	v_cndmask_b32_e64 v87, 0, 1, s[2:3]
	v_cmp_ne_u32_e64 s[16:17], 0, v87
	s_nop 1
	v_writelane_b32 v92, s16, 5
	v_writelane_b32 v93, s17, 5
	v_cmp_ge_u32_e64 s[16:17], v170, v153
	v_cmp_ne_u32_e64 s[20:21], 0, v170
	s_and_b64 s[2:3], s[20:21], s[16:17]
	v_cndmask_b32_e64 v87, 0, 1, s[2:3]
	v_cmp_ne_u32_e64 s[16:17], 0, v87
	v_cmp_ne_u32_e64 s[18:19], 0, v169
	s_nop 1
	v_writelane_b32 v92, s16, 6
	v_writelane_b32 v93, s17, 6
	v_cmp_ge_u32_e64 s[16:17], v169, v153
	s_and_b64 s[2:3], s[18:19], s[16:17]
	v_cndmask_b32_e64 v87, 0, 1, s[2:3]
	v_cmp_ne_u32_e64 s[16:17], 0, v87
	s_nop 1
	v_writelane_b32 v92, s16, 7
	v_writelane_b32 v93, s17, 7
	v_cmp_ge_u32_e64 s[16:17], v172, v153
	v_cmp_ne_u32_e64 s[20:21], 0, v172
	s_and_b64 s[2:3], s[20:21], s[16:17]
	v_cndmask_b32_e64 v87, 0, 1, s[2:3]
	v_cmp_ne_u32_e64 s[16:17], 0, v87
	v_cmp_ne_u32_e64 s[18:19], 0, v171
	s_nop 1
	v_writelane_b32 v92, s16, 8
	v_writelane_b32 v93, s17, 8
	v_cmp_ge_u32_e64 s[16:17], v171, v153
	s_and_b64 s[2:3], s[18:19], s[16:17]
	v_cndmask_b32_e64 v87, 0, 1, s[2:3]
	v_cmp_ne_u32_e64 s[16:17], 0, v87
	s_nop 1
	v_writelane_b32 v92, s16, 9
	v_writelane_b32 v93, s17, 9
	v_cmp_ge_u32_e64 s[16:17], v174, v153
	v_cmp_ne_u32_e64 s[20:21], 0, v174
	s_and_b64 s[2:3], s[20:21], s[16:17]
	v_cndmask_b32_e64 v87, 0, 1, s[2:3]
	v_cmp_ne_u32_e64 s[16:17], 0, v87
	v_cmp_ne_u32_e64 s[18:19], 0, v173
	s_nop 1
	v_writelane_b32 v92, s16, 10
	v_writelane_b32 v93, s17, 10
	v_cmp_ge_u32_e64 s[16:17], v173, v153
	s_and_b64 s[2:3], s[18:19], s[16:17]
	v_cndmask_b32_e64 v87, 0, 1, s[2:3]
	v_cmp_ne_u32_e64 s[16:17], 0, v87
	s_nop 1
	v_writelane_b32 v92, s16, 11
	v_writelane_b32 v93, s17, 11
	v_cmp_ge_u32_e64 s[16:17], v176, v153
	v_cmp_ne_u32_e64 s[20:21], 0, v176
	s_and_b64 s[2:3], s[20:21], s[16:17]
	v_cndmask_b32_e64 v87, 0, 1, s[2:3]
	v_cmp_ne_u32_e64 s[16:17], 0, v87
	v_cmp_ne_u32_e64 s[18:19], 0, v175
	s_nop 1
	v_writelane_b32 v92, s16, 12
	v_writelane_b32 v93, s17, 12
	v_cmp_ge_u32_e64 s[16:17], v175, v153
	s_and_b64 s[2:3], s[18:19], s[16:17]
	v_cndmask_b32_e64 v87, 0, 1, s[2:3]
	v_cmp_ne_u32_e64 s[16:17], 0, v87
	s_nop 1
	v_writelane_b32 v92, s16, 13
	v_writelane_b32 v93, s17, 13
	v_cmp_ge_u32_e64 s[16:17], v178, v153
	v_cmp_ne_u32_e64 s[20:21], 0, v178
	s_and_b64 s[2:3], s[20:21], s[16:17]
	v_cndmask_b32_e64 v87, 0, 1, s[2:3]
	v_cmp_ne_u32_e64 s[16:17], 0, v87
	v_cmp_ne_u32_e64 s[18:19], 0, v177
	s_nop 1
	v_writelane_b32 v92, s16, 14
	v_writelane_b32 v93, s17, 14
	v_cmp_ge_u32_e64 s[16:17], v177, v153
	s_and_b64 s[2:3], s[18:19], s[16:17]
	v_cndmask_b32_e64 v87, 0, 1, s[2:3]
	v_cmp_ne_u32_e64 s[16:17], 0, v87
	s_nop 1
	v_writelane_b32 v92, s16, 15
	v_writelane_b32 v93, s17, 15
	s_cmp_le_u32 m0, 5
	s_cbranch_scc1 .Lsel_fin_tail
	v_cmp_ge_u32_e64 s[16:17], v180, v153
	v_cmp_ne_u32_e64 s[20:21], 0, v180
	s_and_b64 s[2:3], s[20:21], s[16:17]
	v_cndmask_b32_e64 v87, 0, 1, s[2:3]
	v_cmp_ne_u32_e64 s[16:17], 0, v87
	v_cmp_ne_u32_e64 s[18:19], 0, v179
	s_nop 1
	v_writelane_b32 v92, s16, 16
	v_writelane_b32 v93, s17, 16
	v_cmp_ge_u32_e64 s[16:17], v179, v153
	s_and_b64 s[2:3], s[18:19], s[16:17]
	v_cndmask_b32_e64 v87, 0, 1, s[2:3]
	v_cmp_ne_u32_e64 s[16:17], 0, v87
	s_nop 1
	v_writelane_b32 v92, s16, 17
	v_writelane_b32 v93, s17, 17
	v_cmp_ge_u32_e64 s[16:17], v182, v153
	v_cmp_ne_u32_e64 s[20:21], 0, v182
	s_and_b64 s[2:3], s[20:21], s[16:17]
	v_cndmask_b32_e64 v87, 0, 1, s[2:3]
	v_cmp_ne_u32_e64 s[16:17], 0, v87
	v_cmp_ne_u32_e64 s[18:19], 0, v181
	s_nop 1
	v_writelane_b32 v92, s16, 18
	v_writelane_b32 v93, s17, 18
	v_cmp_ge_u32_e64 s[16:17], v181, v153
	s_and_b64 s[2:3], s[18:19], s[16:17]
	v_cndmask_b32_e64 v87, 0, 1, s[2:3]
	v_cmp_ne_u32_e64 s[16:17], 0, v87
	s_nop 1
	v_writelane_b32 v92, s16, 19
	v_writelane_b32 v93, s17, 19
	v_cmp_ge_u32_e64 s[16:17], v184, v153
	v_cmp_ne_u32_e64 s[20:21], 0, v184
	s_and_b64 s[2:3], s[20:21], s[16:17]
	v_cndmask_b32_e64 v87, 0, 1, s[2:3]
	v_cmp_ne_u32_e64 s[16:17], 0, v87
	v_cmp_ne_u32_e64 s[18:19], 0, v183
	s_nop 1
	v_writelane_b32 v92, s16, 20
	v_writelane_b32 v93, s17, 20
	v_cmp_ge_u32_e64 s[16:17], v183, v153
	s_and_b64 s[2:3], s[18:19], s[16:17]
	v_cndmask_b32_e64 v87, 0, 1, s[2:3]
	v_cmp_ne_u32_e64 s[16:17], 0, v87
	s_nop 1
	v_writelane_b32 v92, s16, 21
	v_writelane_b32 v93, s17, 21
	v_cmp_ge_u32_e64 s[16:17], v186, v153
	v_cmp_ne_u32_e64 s[20:21], 0, v186
	s_and_b64 s[2:3], s[20:21], s[16:17]
	v_cndmask_b32_e64 v87, 0, 1, s[2:3]
	v_cmp_ne_u32_e64 s[16:17], 0, v87
	v_cmp_ne_u32_e64 s[18:19], 0, v185
	s_nop 1
	v_writelane_b32 v92, s16, 22
	v_writelane_b32 v93, s17, 22
	v_cmp_ge_u32_e64 s[16:17], v185, v153
	s_and_b64 s[2:3], s[18:19], s[16:17]
	v_cndmask_b32_e64 v87, 0, 1, s[2:3]
	v_cmp_ne_u32_e64 s[16:17], 0, v87
	s_nop 1
	v_writelane_b32 v92, s16, 23
	v_writelane_b32 v93, s17, 23
	v_cmp_ge_u32_e64 s[16:17], v188, v153
	v_cmp_ne_u32_e64 s[20:21], 0, v188
	s_and_b64 s[2:3], s[20:21], s[16:17]
	v_cndmask_b32_e64 v87, 0, 1, s[2:3]
	v_cmp_ne_u32_e64 s[16:17], 0, v87
	v_cmp_ne_u32_e64 s[18:19], 0, v187
	s_nop 1
	v_writelane_b32 v92, s16, 24
	v_writelane_b32 v93, s17, 24
	v_cmp_ge_u32_e64 s[16:17], v187, v153
	s_and_b64 s[2:3], s[18:19], s[16:17]
	v_cndmask_b32_e64 v87, 0, 1, s[2:3]
	v_cmp_ne_u32_e64 s[16:17], 0, v87
	s_nop 1
	v_writelane_b32 v92, s16, 25
	v_writelane_b32 v93, s17, 25
	v_cmp_ge_u32_e64 s[16:17], v190, v153
	v_cmp_ne_u32_e64 s[20:21], 0, v190
	s_and_b64 s[2:3], s[20:21], s[16:17]
	v_cndmask_b32_e64 v87, 0, 1, s[2:3]
	v_cmp_ne_u32_e64 s[16:17], 0, v87
	v_cmp_ne_u32_e64 s[18:19], 0, v189
	s_nop 1
	v_writelane_b32 v92, s16, 26
	v_writelane_b32 v93, s17, 26
	v_cmp_ge_u32_e64 s[16:17], v189, v153
	s_and_b64 s[2:3], s[18:19], s[16:17]
	v_cndmask_b32_e64 v87, 0, 1, s[2:3]
	v_cmp_ne_u32_e64 s[16:17], 0, v87
	s_nop 1
	v_writelane_b32 v92, s16, 27
	v_writelane_b32 v93, s17, 27
	v_cmp_ge_u32_e64 s[16:17], v192, v153
	v_cmp_ne_u32_e64 s[20:21], 0, v192
	s_and_b64 s[2:3], s[20:21], s[16:17]
	v_cndmask_b32_e64 v87, 0, 1, s[2:3]
	v_cmp_ne_u32_e64 s[16:17], 0, v87
	v_cmp_ne_u32_e64 s[18:19], 0, v191
	s_nop 1
	v_writelane_b32 v92, s16, 28
	v_writelane_b32 v93, s17, 28
	v_cmp_ge_u32_e64 s[16:17], v191, v153
	s_and_b64 s[2:3], s[18:19], s[16:17]
	v_cndmask_b32_e64 v87, 0, 1, s[2:3]
	v_cmp_ne_u32_e64 s[16:17], 0, v87
	s_nop 1
	v_writelane_b32 v92, s16, 29
	v_writelane_b32 v93, s17, 29
	v_cmp_ge_u32_e64 s[16:17], v194, v153
	v_cmp_ne_u32_e64 s[20:21], 0, v194
	s_and_b64 s[2:3], s[20:21], s[16:17]
	v_cndmask_b32_e64 v87, 0, 1, s[2:3]
	v_cmp_ne_u32_e64 s[16:17], 0, v87
	v_cmp_ne_u32_e64 s[18:19], 0, v193
	s_nop 1
	v_writelane_b32 v92, s16, 30
	v_writelane_b32 v93, s17, 30
	v_cmp_ge_u32_e64 s[16:17], v193, v153
	s_and_b64 s[2:3], s[18:19], s[16:17]
	v_cndmask_b32_e64 v87, 0, 1, s[2:3]
	v_cmp_ne_u32_e64 s[16:17], 0, v87
	s_nop 1
	v_writelane_b32 v92, s16, 31
	v_writelane_b32 v93, s17, 31
	s_cmp_le_u32 m0, 6
	s_cbranch_scc1 .Lsel_fin_tail
	v_cmp_ge_u32_e64 s[16:17], v196, v153
	v_cmp_ne_u32_e64 s[20:21], 0, v196
	s_and_b64 s[2:3], s[20:21], s[16:17]
	v_cndmask_b32_e64 v87, 0, 1, s[2:3]
	v_cmp_ne_u32_e64 s[16:17], 0, v87
	v_cmp_ne_u32_e64 s[18:19], 0, v195
	s_nop 1
	v_writelane_b32 v92, s16, 32
	v_writelane_b32 v93, s17, 32
	v_cmp_ge_u32_e64 s[16:17], v195, v153
	s_and_b64 s[2:3], s[18:19], s[16:17]
	v_cndmask_b32_e64 v87, 0, 1, s[2:3]
	v_cmp_ne_u32_e64 s[16:17], 0, v87
	s_nop 1
	v_writelane_b32 v92, s16, 33
	v_writelane_b32 v93, s17, 33
	v_cmp_ge_u32_e64 s[16:17], v198, v153
	v_cmp_ne_u32_e64 s[20:21], 0, v198
	s_and_b64 s[2:3], s[20:21], s[16:17]
	v_cndmask_b32_e64 v87, 0, 1, s[2:3]
	v_cmp_ne_u32_e64 s[16:17], 0, v87
	v_cmp_ne_u32_e64 s[18:19], 0, v197
	s_nop 1
	v_writelane_b32 v92, s16, 34
	v_writelane_b32 v93, s17, 34
	v_cmp_ge_u32_e64 s[16:17], v197, v153
	s_and_b64 s[2:3], s[18:19], s[16:17]
	v_cndmask_b32_e64 v87, 0, 1, s[2:3]
	v_cmp_ne_u32_e64 s[16:17], 0, v87
	s_nop 1
	v_writelane_b32 v92, s16, 35
	v_writelane_b32 v93, s17, 35
	v_cmp_ge_u32_e64 s[16:17], v200, v153
	v_cmp_ne_u32_e64 s[20:21], 0, v200
	s_and_b64 s[2:3], s[20:21], s[16:17]
	v_cndmask_b32_e64 v87, 0, 1, s[2:3]
	v_cmp_ne_u32_e64 s[16:17], 0, v87
	v_cmp_ne_u32_e64 s[18:19], 0, v199
	s_nop 1
	v_writelane_b32 v92, s16, 36
	v_writelane_b32 v93, s17, 36
	v_cmp_ge_u32_e64 s[16:17], v199, v153
	s_and_b64 s[2:3], s[18:19], s[16:17]
	v_cndmask_b32_e64 v87, 0, 1, s[2:3]
	v_cmp_ne_u32_e64 s[16:17], 0, v87
	s_nop 1
	v_writelane_b32 v92, s16, 37
	v_writelane_b32 v93, s17, 37
	v_cmp_ge_u32_e64 s[16:17], v202, v153
	v_cmp_ne_u32_e64 s[20:21], 0, v202
	s_and_b64 s[2:3], s[20:21], s[16:17]
	v_cndmask_b32_e64 v87, 0, 1, s[2:3]
	v_cmp_ne_u32_e64 s[16:17], 0, v87
	v_cmp_ne_u32_e64 s[18:19], 0, v201
	s_nop 1
	v_writelane_b32 v92, s16, 38
	v_writelane_b32 v93, s17, 38
	v_cmp_ge_u32_e64 s[16:17], v201, v153
	s_and_b64 s[2:3], s[18:19], s[16:17]
	v_cndmask_b32_e64 v87, 0, 1, s[2:3]
	v_cmp_ne_u32_e64 s[16:17], 0, v87
	s_nop 1
	v_writelane_b32 v92, s16, 39
	v_writelane_b32 v93, s17, 39
	v_cmp_ge_u32_e64 s[16:17], v204, v153
	v_cmp_ne_u32_e64 s[20:21], 0, v204
	s_and_b64 s[2:3], s[20:21], s[16:17]
	v_cndmask_b32_e64 v87, 0, 1, s[2:3]
	v_cmp_ne_u32_e64 s[16:17], 0, v87
	v_cmp_ne_u32_e64 s[18:19], 0, v203
	s_nop 1
	v_writelane_b32 v92, s16, 40
	v_writelane_b32 v93, s17, 40
	v_cmp_ge_u32_e64 s[16:17], v203, v153
	s_and_b64 s[2:3], s[18:19], s[16:17]
	v_cndmask_b32_e64 v87, 0, 1, s[2:3]
	v_cmp_ne_u32_e64 s[16:17], 0, v87
	s_nop 1
	v_writelane_b32 v92, s16, 41
	v_writelane_b32 v93, s17, 41
	v_cmp_ge_u32_e64 s[16:17], v206, v153
	v_cmp_ne_u32_e64 s[20:21], 0, v206
	s_and_b64 s[2:3], s[20:21], s[16:17]
	v_cndmask_b32_e64 v87, 0, 1, s[2:3]
	v_cmp_ne_u32_e64 s[16:17], 0, v87
	v_cmp_ne_u32_e64 s[18:19], 0, v205
	s_nop 1
	v_writelane_b32 v92, s16, 42
	v_writelane_b32 v93, s17, 42
	v_cmp_ge_u32_e64 s[16:17], v205, v153
	s_and_b64 s[2:3], s[18:19], s[16:17]
	v_cndmask_b32_e64 v87, 0, 1, s[2:3]
	v_cmp_ne_u32_e64 s[16:17], 0, v87
	s_nop 1
	v_writelane_b32 v92, s16, 43
	v_writelane_b32 v93, s17, 43
	v_cmp_ge_u32_e64 s[16:17], v222, v153
	v_cmp_ne_u32_e64 s[20:21], 0, v222
	s_and_b64 s[2:3], s[20:21], s[16:17]
	v_cndmask_b32_e64 v87, 0, 1, s[2:3]
	v_cmp_ne_u32_e64 s[16:17], 0, v87
	v_cmp_ne_u32_e64 s[18:19], 0, v207
	s_nop 1
	v_writelane_b32 v92, s16, 44
	v_writelane_b32 v93, s17, 44
	v_cmp_ge_u32_e64 s[16:17], v207, v153
	s_and_b64 s[2:3], s[18:19], s[16:17]
	v_cndmask_b32_e64 v87, 0, 1, s[2:3]
	v_cmp_ne_u32_e64 s[16:17], 0, v87
	s_nop 1
	v_writelane_b32 v92, s16, 45
	v_writelane_b32 v93, s17, 45
	v_cmp_ge_u32_e64 s[16:17], v224, v153
	v_cmp_ne_u32_e64 s[20:21], 0, v224
	s_and_b64 s[2:3], s[20:21], s[16:17]
	v_cndmask_b32_e64 v87, 0, 1, s[2:3]
	v_cmp_ne_u32_e64 s[16:17], 0, v87
	v_cmp_ne_u32_e64 s[18:19], 0, v223
	s_nop 1
	v_writelane_b32 v92, s16, 46
	v_writelane_b32 v93, s17, 46
	v_cmp_ge_u32_e64 s[16:17], v223, v153
	s_and_b64 s[2:3], s[18:19], s[16:17]
	v_cndmask_b32_e64 v87, 0, 1, s[2:3]
	v_cmp_ne_u32_e64 s[16:17], 0, v87
	s_nop 1
	v_writelane_b32 v92, s16, 47
	v_writelane_b32 v93, s17, 47
	s_cmp_le_u32 m0, 7
	s_cbranch_scc1 .Lsel_fin_tail
	v_cmp_ge_u32_e64 s[16:17], v226, v153
	v_cmp_ne_u32_e64 s[20:21], 0, v226
	s_and_b64 s[2:3], s[20:21], s[16:17]
	v_cndmask_b32_e64 v87, 0, 1, s[2:3]
	v_cmp_ne_u32_e64 s[16:17], 0, v87
	v_cmp_ne_u32_e64 s[18:19], 0, v225
	s_nop 1
	v_writelane_b32 v92, s16, 48
	v_writelane_b32 v93, s17, 48
	v_cmp_ge_u32_e64 s[16:17], v225, v153
	s_and_b64 s[2:3], s[18:19], s[16:17]
	v_cndmask_b32_e64 v87, 0, 1, s[2:3]
	v_cmp_ne_u32_e64 s[16:17], 0, v87
	s_nop 1
	v_writelane_b32 v92, s16, 49
	v_writelane_b32 v93, s17, 49
	v_cmp_ge_u32_e64 s[16:17], v228, v153
	v_cmp_ne_u32_e64 s[20:21], 0, v228
	s_and_b64 s[2:3], s[20:21], s[16:17]
	v_cndmask_b32_e64 v87, 0, 1, s[2:3]
	v_cmp_ne_u32_e64 s[16:17], 0, v87
	v_cmp_ne_u32_e64 s[18:19], 0, v227
	s_nop 1
	v_writelane_b32 v92, s16, 50
	v_writelane_b32 v93, s17, 50
	v_cmp_ge_u32_e64 s[16:17], v227, v153
	s_and_b64 s[2:3], s[18:19], s[16:17]
	v_cndmask_b32_e64 v87, 0, 1, s[2:3]
	v_cmp_ne_u32_e64 s[16:17], 0, v87
	s_nop 1
	v_writelane_b32 v92, s16, 51
	v_writelane_b32 v93, s17, 51
	v_cmp_ge_u32_e64 s[16:17], v230, v153
	v_cmp_ne_u32_e64 s[20:21], 0, v230
	s_and_b64 s[2:3], s[20:21], s[16:17]
	v_cndmask_b32_e64 v87, 0, 1, s[2:3]
	v_cmp_ne_u32_e64 s[16:17], 0, v87
	v_cmp_ne_u32_e64 s[18:19], 0, v229
	s_nop 1
	v_writelane_b32 v92, s16, 52
	v_writelane_b32 v93, s17, 52
	v_cmp_ge_u32_e64 s[16:17], v229, v153
	s_and_b64 s[2:3], s[18:19], s[16:17]
	v_cndmask_b32_e64 v87, 0, 1, s[2:3]
	v_cmp_ne_u32_e64 s[16:17], 0, v87
	s_nop 1
	v_writelane_b32 v92, s16, 53
	v_writelane_b32 v93, s17, 53
	v_cmp_ge_u32_e64 s[16:17], v232, v153
	v_cmp_ne_u32_e64 s[20:21], 0, v232
	s_and_b64 s[2:3], s[20:21], s[16:17]
	v_cndmask_b32_e64 v87, 0, 1, s[2:3]
	v_cmp_ne_u32_e64 s[16:17], 0, v87
	v_cmp_ne_u32_e64 s[18:19], 0, v231
	s_nop 1
	v_writelane_b32 v92, s16, 54
	v_writelane_b32 v93, s17, 54
	v_cmp_ge_u32_e64 s[16:17], v231, v153
	s_and_b64 s[2:3], s[18:19], s[16:17]
	v_cndmask_b32_e64 v87, 0, 1, s[2:3]
	v_cmp_ne_u32_e64 s[16:17], 0, v87
	s_nop 1
	v_writelane_b32 v92, s16, 55
	v_writelane_b32 v93, s17, 55
	v_cmp_ge_u32_e64 s[16:17], v234, v153
	v_cmp_ne_u32_e64 s[20:21], 0, v234
	s_and_b64 s[2:3], s[20:21], s[16:17]
	v_cndmask_b32_e64 v87, 0, 1, s[2:3]
	v_cmp_ne_u32_e64 s[16:17], 0, v87
	v_cmp_ne_u32_e64 s[18:19], 0, v233
	s_nop 1
	v_writelane_b32 v92, s16, 56
	v_writelane_b32 v93, s17, 56
	v_cmp_ge_u32_e64 s[16:17], v233, v153
	s_and_b64 s[2:3], s[18:19], s[16:17]
	v_cndmask_b32_e64 v87, 0, 1, s[2:3]
	v_cmp_ne_u32_e64 s[16:17], 0, v87
	s_nop 1
	v_writelane_b32 v92, s16, 57
	v_writelane_b32 v93, s17, 57
	v_cmp_ge_u32_e64 s[16:17], v236, v153
	v_cmp_ne_u32_e64 s[20:21], 0, v236
	s_and_b64 s[2:3], s[20:21], s[16:17]
	v_cndmask_b32_e64 v87, 0, 1, s[2:3]
	v_cmp_ne_u32_e64 s[16:17], 0, v87
	v_cmp_ne_u32_e64 s[18:19], 0, v235
	s_nop 1
	v_writelane_b32 v92, s16, 58
	v_writelane_b32 v93, s17, 58
	v_cmp_ge_u32_e64 s[16:17], v235, v153
	s_and_b64 s[2:3], s[18:19], s[16:17]
	v_cndmask_b32_e64 v87, 0, 1, s[2:3]
	v_cmp_ne_u32_e64 s[16:17], 0, v87
	s_nop 1
	v_writelane_b32 v92, s16, 59
	v_writelane_b32 v93, s17, 59
	v_cmp_ge_u32_e64 s[16:17], v238, v153
	v_cmp_ne_u32_e64 s[20:21], 0, v238
	s_and_b64 s[2:3], s[20:21], s[16:17]
	v_cndmask_b32_e64 v87, 0, 1, s[2:3]
	v_cmp_ne_u32_e64 s[16:17], 0, v87
	v_cmp_ne_u32_e64 s[18:19], 0, v237
	s_nop 1
	v_writelane_b32 v92, s16, 60
	v_writelane_b32 v93, s17, 60
	v_cmp_ge_u32_e64 s[16:17], v237, v153
	s_and_b64 s[2:3], s[18:19], s[16:17]
	v_cndmask_b32_e64 v87, 0, 1, s[2:3]
	v_cmp_ne_u32_e64 s[16:17], 0, v87
	s_nop 1
	v_writelane_b32 v92, s16, 61
	v_writelane_b32 v93, s17, 61
	v_cmp_ge_u32_e64 s[16:17], v239, v153
	v_cmp_ne_u32_e64 s[20:21], 0, v239
	s_and_b64 s[2:3], s[20:21], s[16:17]
	v_cndmask_b32_e64 v87, 0, 1, s[2:3]
	v_cmp_ne_u32_e64 s[16:17], 0, v87
	v_cmp_ne_u32_e64 s[18:19], 0, v168
	s_nop 1
	v_writelane_b32 v92, s16, 62
	v_writelane_b32 v93, s17, 62
	v_cmp_ge_u32_e64 s[16:17], v168, v153
	s_and_b64 s[2:3], s[18:19], s[16:17]
	v_cndmask_b32_e64 v87, 0, 1, s[2:3]
	v_cmp_ne_u32_e64 s[16:17], 0, v87
	v_mov_b32_e32 v87, v0
	v_lshl_add_u64 v[90:91], v[90:91], 0, v[86:87]
	s_nop 1
	v_writelane_b32 v92, s16, 63
	v_writelane_b32 v93, s17, 63
	global_store_dwordx2 v[90:91], v[88:89], off
	global_store_dwordx2 v[90:91], v[92:93], off offset:512
	s_branch .LBB0_671
.Lsel_fin_tail:
	v_mov_b32_e32 v87, v0
	v_lshl_add_u64 v[90:91], v[90:91], 0, v[86:87]
	global_store_dwordx2 v[90:91], v[88:89], off
	global_store_dwordx2 v[90:91], v[92:93], off offset:512
	s_branch .LBB0_671
